# v76: GEMM MFMA quads reordered so consecutive MFMAs share a source operand (operand-reuse order; bit-identical)
# baseline (speedup 1.0000x reference)
.LBB0_179:
	s_ashr_i32 s47, s46, 31
	s_lshl_b64 s[48:49], s[46:47], 19
	s_add_u32 s48, s26, s48
	s_addc_u32 s49, s27, s49
	s_and_b64 s[50:51], s[44:45], exec
	s_cselect_b32 s47, s49, s63
	s_cselect_b32 s82, s48, s62
	s_ashr_i32 s21, s20, 31
	s_lshl_b64 s[50:51], s[20:21], 19
	s_add_u32 s50, s59, s50
	s_addc_u32 s51, s66, s51
	s_and_b64 s[84:85], s[44:45], exec
	s_cselect_b32 s21, s51, s61
	s_cselect_b32 s83, s50, s60
	s_add_u32 s89, s60, 0x100
	s_addc_u32 s84, s61, 0
	s_add_u32 s60, s62, 0x40080
	s_addc_u32 s61, s63, 0
	s_mov_b32 s85, -2
	s_add_u32 s62, s60, 0xfffc0080
	s_addc_u32 s63, s61, -1
	s_cmp_eq_u32 s85, 12
	s_cselect_b32 vcc_hi, s47, s63
	s_cselect_b32 vcc_lo, s82, s62
	s_cselect_b32 s63, s21, s84
	s_cselect_b32 s62, s83, s89
	v_lshl_add_u64 v[142:143], s[60:61], 0, v[136:137]
	s_add_i32 m0, s68, 0xc000
	global_load_lds_dwordx4 v[142:143], off
	v_lshl_add_u64 v[142:143], s[60:61], 0, v[134:135]
	s_add_i32 m0, s68, 0xe000
	s_nop 0
	global_load_lds_dwordx4 v[142:143], off
	s_waitcnt vmcnt(8)
	s_waitcnt lgkmcnt(0)
	s_barrier
	s_setprio 1
	s_waitcnt lgkmcnt(0)
	v_mfma_f32_16x16x32_bf16 v[124:127], v[138:141], v[210:213], 0
	v_mfma_f32_16x16x32_bf16 v[116:119], v[176:179], v[210:213], 0
	v_mfma_f32_16x16x32_bf16 v[108:111], v[138:141], v[218:221], 0
	v_mfma_f32_16x16x32_bf16 v[100:103], v[176:179], v[218:221], 0
	v_mfma_f32_16x16x32_bf16 v[92:95], v[138:141], v[228:231], 0
	v_mfma_f32_16x16x32_bf16 v[84:87], v[176:179], v[228:231], 0
	v_mfma_f32_16x16x32_bf16 v[76:79], v[138:141], v[236:239], 0
	v_mfma_f32_16x16x32_bf16 v[68:71], v[176:179], v[236:239], 0
	v_mfma_f32_16x16x32_bf16 v[124:127], v[172:175], v[214:217], v[124:127]
	v_mfma_f32_16x16x32_bf16 v[116:119], v[180:183], v[214:217], v[116:119]
	v_mfma_f32_16x16x32_bf16 v[100:103], v[180:183], v[224:227], v[100:103]
	v_mfma_f32_16x16x32_bf16 v[108:111], v[172:175], v[224:227], v[108:111]
	v_mfma_f32_16x16x32_bf16 v[92:95], v[172:175], v[232:235], v[92:95]
	v_mfma_f32_16x16x32_bf16 v[84:87], v[180:183], v[232:235], v[84:87]
	v_mfma_f32_16x16x32_bf16 v[68:71], v[180:183], v[240:243], v[68:71]
	v_mfma_f32_16x16x32_bf16 v[76:79], v[172:175], v[240:243], v[76:79]
	s_setprio 0
	s_setprio 1
	v_mfma_f32_16x16x32_bf16 v[120:123], v[184:187], v[210:213], 0
	v_mfma_f32_16x16x32_bf16 v[112:115], v[192:195], v[210:213], 0
	v_mfma_f32_16x16x32_bf16 v[104:107], v[184:187], v[218:221], 0
	v_mfma_f32_16x16x32_bf16 v[96:99], v[192:195], v[218:221], 0
	v_mfma_f32_16x16x32_bf16 v[88:91], v[184:187], v[228:231], 0
	v_mfma_f32_16x16x32_bf16 v[80:83], v[192:195], v[228:231], 0
	v_mfma_f32_16x16x32_bf16 v[72:75], v[184:187], v[236:239], 0
	v_mfma_f32_16x16x32_bf16 v[64:67], v[192:195], v[236:239], 0
	v_mfma_f32_16x16x32_bf16 v[120:123], v[188:191], v[214:217], v[120:123]
	v_mfma_f32_16x16x32_bf16 v[112:115], v[196:199], v[214:217], v[112:115]
	v_mfma_f32_16x16x32_bf16 v[96:99], v[196:199], v[224:227], v[96:99]
	v_mfma_f32_16x16x32_bf16 v[104:107], v[188:191], v[224:227], v[104:107]
	v_mfma_f32_16x16x32_bf16 v[88:91], v[188:191], v[232:235], v[88:91]
	v_mfma_f32_16x16x32_bf16 v[80:83], v[196:199], v[232:235], v[80:83]
	v_mfma_f32_16x16x32_bf16 v[64:67], v[196:199], v[240:243], v[64:67]
	v_mfma_f32_16x16x32_bf16 v[72:75], v[188:191], v[240:243], v[72:75]
	s_setprio 0
	s_barrier
	s_add_i32 s86, s86, s67
	v_lshl_add_u64 v[142:143], s[62:63], 0, v[152:153]
	s_mov_b32 m0, s86
	ds_read_b128 v[210:213], v148 offset:16384
	ds_read_b128 v[214:217], v148 offset:17408
	ds_read_b128 v[218:221], v148 offset:18432
	ds_read_b128 v[224:227], v148 offset:19456
	ds_read_b128 v[228:231], v148 offset:20480
	ds_read_b128 v[232:235], v148 offset:21504
	ds_read_b128 v[236:239], v148 offset:22528
	ds_read_b128 v[240:243], v148 offset:23552
	global_load_lds_dwordx4 v[142:143], off
	s_add_i32 m0, s86, 0x2000
	s_add_u32 s86, s62, 0x40000
	v_lshl_add_u64 v[150:151], s[62:63], 0, v[128:129]
	s_addc_u32 s87, s63, 0
	s_add_i32 s92, s92, s67
	global_load_lds_dwordx4 v[150:151], off
	v_lshl_add_u64 v[244:245], s[86:87], 0, v[152:153]
	s_mov_b32 m0, s92
	v_lshl_add_u64 v[246:247], vcc, 0, v[130:131]
	global_load_lds_dwordx4 v[244:245], off
	v_lshl_add_u64 v[244:245], s[86:87], 0, v[128:129]
	s_add_i32 m0, s92, 0x2000
	s_nop 0
	global_load_lds_dwordx4 v[244:245], off
	v_lshl_add_u64 v[244:245], vcc, 0, v[132:133]
	s_mov_b32 m0, s68
	s_nop 0
	global_load_lds_dwordx4 v[244:245], off
	s_mov_b32 m0, s69
	s_nop 0
	global_load_lds_dwordx4 v[246:247], off
	s_waitcnt vmcnt(8)
	s_waitcnt lgkmcnt(0)
	s_barrier
	s_setprio 1
	s_waitcnt lgkmcnt(0)
	v_mfma_f32_16x16x32_bf16 v[60:63], v[138:141], v[210:213], 0
	v_mfma_f32_16x16x32_bf16 v[52:55], v[176:179], v[210:213], 0
	v_mfma_f32_16x16x32_bf16 v[44:47], v[138:141], v[218:221], 0
	v_mfma_f32_16x16x32_bf16 v[36:39], v[176:179], v[218:221], 0
	v_mfma_f32_16x16x32_bf16 v[28:31], v[138:141], v[228:231], 0
	v_mfma_f32_16x16x32_bf16 v[20:23], v[176:179], v[228:231], 0
	v_mfma_f32_16x16x32_bf16 v[12:15], v[138:141], v[236:239], 0
	v_mfma_f32_16x16x32_bf16 v[4:7], v[176:179], v[236:239], 0
	v_mfma_f32_16x16x32_bf16 v[60:63], v[172:175], v[214:217], v[60:63]
	v_mfma_f32_16x16x32_bf16 v[52:55], v[180:183], v[214:217], v[52:55]
	v_mfma_f32_16x16x32_bf16 v[36:39], v[180:183], v[224:227], v[36:39]
	v_mfma_f32_16x16x32_bf16 v[44:47], v[172:175], v[224:227], v[44:47]
	v_mfma_f32_16x16x32_bf16 v[28:31], v[172:175], v[232:235], v[28:31]
	v_mfma_f32_16x16x32_bf16 v[20:23], v[180:183], v[232:235], v[20:23]
	v_mfma_f32_16x16x32_bf16 v[4:7], v[180:183], v[240:243], v[4:7]
	v_mfma_f32_16x16x32_bf16 v[12:15], v[172:175], v[240:243], v[12:15]
	s_setprio 0
	s_setprio 1
	v_mfma_f32_16x16x32_bf16 v[56:59], v[184:187], v[210:213], 0
	v_mfma_f32_16x16x32_bf16 v[48:51], v[192:195], v[210:213], 0
	v_mfma_f32_16x16x32_bf16 v[40:43], v[184:187], v[218:221], 0
	v_mfma_f32_16x16x32_bf16 v[32:35], v[192:195], v[218:221], 0
	v_mfma_f32_16x16x32_bf16 v[24:27], v[184:187], v[228:231], 0
	v_mfma_f32_16x16x32_bf16 v[16:19], v[192:195], v[228:231], 0
	v_mfma_f32_16x16x32_bf16 v[8:11], v[184:187], v[236:239], 0
	v_mfma_f32_16x16x32_bf16 v[0:3], v[192:195], v[236:239], 0
	v_mfma_f32_16x16x32_bf16 v[56:59], v[188:191], v[214:217], v[56:59]
	v_mfma_f32_16x16x32_bf16 v[48:51], v[196:199], v[214:217], v[48:51]
	v_mfma_f32_16x16x32_bf16 v[32:35], v[196:199], v[224:227], v[32:35]
	v_mfma_f32_16x16x32_bf16 v[40:43], v[188:191], v[224:227], v[40:43]
	v_mfma_f32_16x16x32_bf16 v[24:27], v[188:191], v[232:235], v[24:27]
	v_mfma_f32_16x16x32_bf16 v[16:19], v[196:199], v[232:235], v[16:19]
	v_mfma_f32_16x16x32_bf16 v[0:3], v[196:199], v[240:243], v[0:3]
	v_mfma_f32_16x16x32_bf16 v[8:11], v[188:191], v[240:243], v[8:11]
	s_setprio 0
	s_barrier
	s_add_i32 s92, 0, 0x18000
	v_add_u32_e32 v149, s92, v145
	s_add_i32 s93, 0, 0x1c000
	ds_read_b128 v[138:141], v149
	ds_read_b128 v[172:175], v149 offset:1024
	ds_read_b128 v[176:179], v149 offset:2048
	ds_read_b128 v[180:183], v149 offset:3072
	v_add_u32_e32 v149, s93, v145
	ds_read_b128 v[184:187], v149
	ds_read_b128 v[188:191], v149 offset:1024
	ds_read_b128 v[192:195], v149 offset:2048
	ds_read_b128 v[196:199], v149 offset:3072
	s_add_u32 s86, vcc_lo, 0x40000
	s_addc_u32 s87, vcc_hi, 0
	s_mov_b32 m0, s74
	v_lshl_add_u64 v[248:249], s[86:87], 0, v[132:133]
	ds_read_b128 v[210:213], v148 offset:32768
	ds_read_b128 v[214:217], v148 offset:33792
	ds_read_b128 v[218:221], v148 offset:34816
	ds_read_b128 v[224:227], v148 offset:35840
	ds_read_b128 v[228:231], v148 offset:36864
	ds_read_b128 v[232:235], v148 offset:37888
	ds_read_b128 v[236:239], v148 offset:38912
	ds_read_b128 v[240:243], v148 offset:39936
	global_load_lds_dwordx4 v[248:249], off
	v_lshl_add_u64 v[248:249], s[86:87], 0, v[130:131]
	s_mov_b32 m0, s75
	s_nop 0
	global_load_lds_dwordx4 v[248:249], off
	s_waitcnt vmcnt(8)
	s_waitcnt lgkmcnt(0)
	s_barrier
	s_setprio 1
	s_waitcnt lgkmcnt(0)
	v_mfma_f32_16x16x32_bf16 v[124:127], v[138:141], v[210:213], v[124:127]
	v_mfma_f32_16x16x32_bf16 v[116:119], v[176:179], v[210:213], v[116:119]
	v_mfma_f32_16x16x32_bf16 v[100:103], v[176:179], v[218:221], v[100:103]
	v_mfma_f32_16x16x32_bf16 v[108:111], v[138:141], v[218:221], v[108:111]
	v_mfma_f32_16x16x32_bf16 v[92:95], v[138:141], v[228:231], v[92:95]
	v_mfma_f32_16x16x32_bf16 v[84:87], v[176:179], v[228:231], v[84:87]
	v_mfma_f32_16x16x32_bf16 v[68:71], v[176:179], v[236:239], v[68:71]
	v_mfma_f32_16x16x32_bf16 v[76:79], v[138:141], v[236:239], v[76:79]
	v_mfma_f32_16x16x32_bf16 v[124:127], v[172:175], v[214:217], v[124:127]
	v_mfma_f32_16x16x32_bf16 v[116:119], v[180:183], v[214:217], v[116:119]
	v_mfma_f32_16x16x32_bf16 v[100:103], v[180:183], v[224:227], v[100:103]
	v_mfma_f32_16x16x32_bf16 v[108:111], v[172:175], v[224:227], v[108:111]
	v_mfma_f32_16x16x32_bf16 v[92:95], v[172:175], v[232:235], v[92:95]
	v_mfma_f32_16x16x32_bf16 v[84:87], v[180:183], v[232:235], v[84:87]
	v_mfma_f32_16x16x32_bf16 v[68:71], v[180:183], v[240:243], v[68:71]
	v_mfma_f32_16x16x32_bf16 v[76:79], v[172:175], v[240:243], v[76:79]
	s_setprio 0
	s_setprio 1
	v_mfma_f32_16x16x32_bf16 v[120:123], v[184:187], v[210:213], v[120:123]
	v_mfma_f32_16x16x32_bf16 v[112:115], v[192:195], v[210:213], v[112:115]
	v_mfma_f32_16x16x32_bf16 v[96:99], v[192:195], v[218:221], v[96:99]
	v_mfma_f32_16x16x32_bf16 v[104:107], v[184:187], v[218:221], v[104:107]
	v_mfma_f32_16x16x32_bf16 v[88:91], v[184:187], v[228:231], v[88:91]
	v_mfma_f32_16x16x32_bf16 v[80:83], v[192:195], v[228:231], v[80:83]
	v_mfma_f32_16x16x32_bf16 v[64:67], v[192:195], v[236:239], v[64:67]
	v_mfma_f32_16x16x32_bf16 v[72:75], v[184:187], v[236:239], v[72:75]
	v_mfma_f32_16x16x32_bf16 v[120:123], v[188:191], v[214:217], v[120:123]
	v_mfma_f32_16x16x32_bf16 v[112:115], v[196:199], v[214:217], v[112:115]
	v_mfma_f32_16x16x32_bf16 v[96:99], v[196:199], v[224:227], v[96:99]
	v_mfma_f32_16x16x32_bf16 v[104:107], v[188:191], v[224:227], v[104:107]
	v_mfma_f32_16x16x32_bf16 v[88:91], v[188:191], v[232:235], v[88:91]
	v_mfma_f32_16x16x32_bf16 v[80:83], v[196:199], v[232:235], v[80:83]
	v_mfma_f32_16x16x32_bf16 v[64:67], v[196:199], v[240:243], v[64:67]
	v_mfma_f32_16x16x32_bf16 v[72:75], v[188:191], v[240:243], v[72:75]
	s_setprio 0
	s_barrier
	s_add_i32 s86, s92, s67
	v_lshl_add_u64 v[142:143], v[142:143], 0, s[22:23]
	s_mov_b32 m0, s86
	ds_read_b128 v[210:213], v148 offset:49152
	ds_read_b128 v[214:217], v148 offset:50176
	ds_read_b128 v[218:221], v148 offset:51200
	ds_read_b128 v[224:227], v148 offset:52224
	ds_read_b128 v[228:231], v148 offset:53248
	ds_read_b128 v[232:235], v148 offset:54272
	ds_read_b128 v[236:239], v148 offset:55296
	ds_read_b128 v[240:243], v148 offset:56320
	global_load_lds_dwordx4 v[142:143], off
	s_add_i32 m0, s86, 0x2000
	s_add_u32 s62, s62, 0x40080
	v_lshl_add_u64 v[142:143], v[150:151], 0, s[22:23]
	s_addc_u32 s63, s63, 0
	s_add_i32 s86, s93, s67
	global_load_lds_dwordx4 v[142:143], off
	v_lshl_add_u64 v[142:143], s[62:63], 0, v[152:153]
	s_mov_b32 m0, s86
	s_nop 0
	global_load_lds_dwordx4 v[142:143], off
	v_lshl_add_u64 v[142:143], s[62:63], 0, v[128:129]
	s_add_i32 m0, s86, 0x2000
	s_nop 0
	global_load_lds_dwordx4 v[142:143], off
	v_lshl_add_u64 v[142:143], v[244:245], 0, s[22:23]
	s_mov_b32 m0, s77
	s_nop 0
	global_load_lds_dwordx4 v[142:143], off
	v_lshl_add_u64 v[142:143], v[246:247], 0, s[22:23]
	s_mov_b32 m0, s78
	s_nop 0
	global_load_lds_dwordx4 v[142:143], off
	s_waitcnt vmcnt(8)
	s_waitcnt lgkmcnt(0)
	s_barrier
	s_setprio 1
	s_waitcnt lgkmcnt(0)
	v_mfma_f32_16x16x32_bf16 v[60:63], v[138:141], v[210:213], v[60:63]
	v_mfma_f32_16x16x32_bf16 v[52:55], v[176:179], v[210:213], v[52:55]
	v_mfma_f32_16x16x32_bf16 v[36:39], v[176:179], v[218:221], v[36:39]
	v_mfma_f32_16x16x32_bf16 v[44:47], v[138:141], v[218:221], v[44:47]
	v_mfma_f32_16x16x32_bf16 v[28:31], v[138:141], v[228:231], v[28:31]
	v_mfma_f32_16x16x32_bf16 v[20:23], v[176:179], v[228:231], v[20:23]
	v_mfma_f32_16x16x32_bf16 v[4:7], v[176:179], v[236:239], v[4:7]
	v_mfma_f32_16x16x32_bf16 v[12:15], v[138:141], v[236:239], v[12:15]
	v_mfma_f32_16x16x32_bf16 v[60:63], v[172:175], v[214:217], v[60:63]
	v_mfma_f32_16x16x32_bf16 v[52:55], v[180:183], v[214:217], v[52:55]
	v_mfma_f32_16x16x32_bf16 v[36:39], v[180:183], v[224:227], v[36:39]
	v_mfma_f32_16x16x32_bf16 v[44:47], v[172:175], v[224:227], v[44:47]
	v_mfma_f32_16x16x32_bf16 v[28:31], v[172:175], v[232:235], v[28:31]
	v_mfma_f32_16x16x32_bf16 v[20:23], v[180:183], v[232:235], v[20:23]
	v_mfma_f32_16x16x32_bf16 v[4:7], v[180:183], v[240:243], v[4:7]
	v_mfma_f32_16x16x32_bf16 v[12:15], v[172:175], v[240:243], v[12:15]
	s_setprio 0
	s_setprio 1
	v_mfma_f32_16x16x32_bf16 v[56:59], v[184:187], v[210:213], v[56:59]
	v_mfma_f32_16x16x32_bf16 v[48:51], v[192:195], v[210:213], v[48:51]
	v_mfma_f32_16x16x32_bf16 v[32:35], v[192:195], v[218:221], v[32:35]
	v_mfma_f32_16x16x32_bf16 v[40:43], v[184:187], v[218:221], v[40:43]
	v_mfma_f32_16x16x32_bf16 v[24:27], v[184:187], v[228:231], v[24:27]
	v_mfma_f32_16x16x32_bf16 v[16:19], v[192:195], v[228:231], v[16:19]
	v_mfma_f32_16x16x32_bf16 v[0:3], v[192:195], v[236:239], v[0:3]
	v_mfma_f32_16x16x32_bf16 v[8:11], v[184:187], v[236:239], v[8:11]
	v_mfma_f32_16x16x32_bf16 v[56:59], v[188:191], v[214:217], v[56:59]
	v_mfma_f32_16x16x32_bf16 v[48:51], v[196:199], v[214:217], v[48:51]
	v_mfma_f32_16x16x32_bf16 v[32:35], v[196:199], v[224:227], v[32:35]
	v_mfma_f32_16x16x32_bf16 v[40:43], v[188:191], v[224:227], v[40:43]
	v_mfma_f32_16x16x32_bf16 v[24:27], v[188:191], v[232:235], v[24:27]
	v_mfma_f32_16x16x32_bf16 v[16:19], v[196:199], v[232:235], v[16:19]
	v_mfma_f32_16x16x32_bf16 v[0:3], v[196:199], v[240:243], v[0:3]
	v_mfma_f32_16x16x32_bf16 v[8:11], v[188:191], v[240:243], v[8:11]
	s_setprio 0
	s_barrier
	s_add_i32 s85, s85, 2
	s_add_u32 s89, s89, 0x100
	s_addc_u32 s84, s84, 0
	s_add_u32 s60, s60, 0x100
	s_addc_u32 s61, s61, 0
	s_cmp_gt_u32 s85, 13
	.p2align	6

.LBB0_280:
	s_add_u32 s84, s18, 0x100
	s_addc_u32 s85, s19, 0
	s_mov_b32 s86, -2
	s_add_u32 vcc_lo, s60, 0x100
	s_addc_u32 vcc_hi, s61, 0
	s_cmp_eq_u32 s86, 40
	s_cselect_b32 s67, s51, vcc_hi
	s_cselect_b32 s66, s50, vcc_lo
	s_cselect_b32 s19, s45, s85
	s_cselect_b32 s18, s44, s84
	v_lshl_add_u64 v[198:199], s[60:61], 0, v[180:181]
	s_add_i32 m0, s69, 0xc000
	global_load_lds_dwordx4 v[198:199], off
	v_lshl_add_u64 v[198:199], s[60:61], 0, v[178:179]
	s_add_i32 m0, s69, 0xe000
	s_nop 0
	global_load_lds_dwordx4 v[198:199], off
	s_waitcnt vmcnt(8)
	s_waitcnt lgkmcnt(0)
	s_barrier
	s_setprio 1
	s_waitcnt lgkmcnt(0)
	v_mfma_f32_16x16x32_bf16 v[124:127], v[128:131], v[190:193], 0
	v_mfma_f32_16x16x32_bf16 v[120:123], v[136:139], v[190:193], 0
	v_mfma_f32_16x16x32_bf16 v[108:111], v[128:131], v[214:217], 0
	v_mfma_f32_16x16x32_bf16 v[104:107], v[136:139], v[214:217], 0
	v_mfma_f32_16x16x32_bf16 v[92:95], v[128:131], v[224:227], 0
	v_mfma_f32_16x16x32_bf16 v[88:91], v[136:139], v[224:227], 0
	v_mfma_f32_16x16x32_bf16 v[76:79], v[128:131], v[232:235], 0
	v_mfma_f32_16x16x32_bf16 v[72:75], v[136:139], v[232:235], 0
	v_mfma_f32_16x16x32_bf16 v[124:127], v[132:135], v[194:197], v[124:127]
	v_mfma_f32_16x16x32_bf16 v[120:123], v[140:143], v[194:197], v[120:123]
	v_mfma_f32_16x16x32_bf16 v[104:107], v[140:143], v[218:221], v[104:107]
	v_mfma_f32_16x16x32_bf16 v[108:111], v[132:135], v[218:221], v[108:111]
	v_mfma_f32_16x16x32_bf16 v[92:95], v[132:135], v[228:231], v[92:95]
	v_mfma_f32_16x16x32_bf16 v[88:91], v[140:143], v[228:231], v[88:91]
	v_mfma_f32_16x16x32_bf16 v[72:75], v[140:143], v[236:239], v[72:75]
	v_mfma_f32_16x16x32_bf16 v[76:79], v[132:135], v[236:239], v[76:79]
	s_setprio 0
	s_setprio 1
	v_mfma_f32_16x16x32_bf16 v[116:119], v[144:147], v[190:193], 0
	v_mfma_f32_16x16x32_bf16 v[112:115], v[182:185], v[190:193], 0
	v_mfma_f32_16x16x32_bf16 v[100:103], v[144:147], v[214:217], 0
	v_mfma_f32_16x16x32_bf16 v[96:99], v[182:185], v[214:217], 0
	v_mfma_f32_16x16x32_bf16 v[84:87], v[144:147], v[224:227], 0
	v_mfma_f32_16x16x32_bf16 v[80:83], v[182:185], v[224:227], 0
	v_mfma_f32_16x16x32_bf16 v[68:71], v[144:147], v[232:235], 0
	v_mfma_f32_16x16x32_bf16 v[64:67], v[182:185], v[232:235], 0
	v_mfma_f32_16x16x32_bf16 v[116:119], v[148:151], v[194:197], v[116:119]
	v_mfma_f32_16x16x32_bf16 v[112:115], v[186:189], v[194:197], v[112:115]
	v_mfma_f32_16x16x32_bf16 v[96:99], v[186:189], v[218:221], v[96:99]
	v_mfma_f32_16x16x32_bf16 v[100:103], v[148:151], v[218:221], v[100:103]
	v_mfma_f32_16x16x32_bf16 v[84:87], v[148:151], v[228:231], v[84:87]
	v_mfma_f32_16x16x32_bf16 v[80:83], v[186:189], v[228:231], v[80:83]
	v_mfma_f32_16x16x32_bf16 v[64:67], v[186:189], v[236:239], v[64:67]
	v_mfma_f32_16x16x32_bf16 v[68:71], v[148:151], v[236:239], v[68:71]
	s_setprio 0
	s_barrier
	s_add_i32 s60, s87, s68
	v_lshl_add_u64 v[198:199], s[18:19], 0, v[152:153]
	s_mov_b32 m0, s60
	ds_read_b128 v[190:193], v212 offset:16384
	ds_read_b128 v[194:197], v212 offset:17408
	ds_read_b128 v[214:217], v212 offset:18432
	ds_read_b128 v[218:221], v212 offset:19456
	ds_read_b128 v[224:227], v212 offset:20480
	ds_read_b128 v[228:231], v212 offset:21504
	ds_read_b128 v[232:235], v212 offset:22528
	ds_read_b128 v[236:239], v212 offset:23552
	global_load_lds_dwordx4 v[198:199], off
	s_add_i32 m0, s60, 0x2000
	s_add_u32 s60, s18, 0xb0000
	v_lshl_add_u64 v[240:241], s[18:19], 0, v[172:173]
	s_addc_u32 s61, s19, 0
	s_add_i32 s87, s92, s68
	global_load_lds_dwordx4 v[240:241], off
	v_lshl_add_u64 v[242:243], s[60:61], 0, v[152:153]
	s_mov_b32 m0, s87
	v_lshl_add_u64 v[244:245], s[66:67], 0, v[174:175]
	global_load_lds_dwordx4 v[242:243], off
	v_lshl_add_u64 v[242:243], s[60:61], 0, v[172:173]
	s_add_i32 m0, s87, 0x2000
	s_nop 0
	global_load_lds_dwordx4 v[242:243], off
	v_lshl_add_u64 v[242:243], s[66:67], 0, v[176:177]
	s_mov_b32 m0, s69
	s_nop 0
	global_load_lds_dwordx4 v[242:243], off
	s_mov_b32 m0, s74
	s_nop 0
	global_load_lds_dwordx4 v[244:245], off
	s_waitcnt vmcnt(8)
	s_waitcnt lgkmcnt(0)
	s_barrier
	s_setprio 1
	s_waitcnt lgkmcnt(0)
	v_mfma_f32_16x16x32_bf16 v[60:63], v[128:131], v[190:193], 0
	v_mfma_f32_16x16x32_bf16 v[56:59], v[136:139], v[190:193], 0
	v_mfma_f32_16x16x32_bf16 v[44:47], v[128:131], v[214:217], 0
	v_mfma_f32_16x16x32_bf16 v[40:43], v[136:139], v[214:217], 0
	v_mfma_f32_16x16x32_bf16 v[28:31], v[128:131], v[224:227], 0
	v_mfma_f32_16x16x32_bf16 v[24:27], v[136:139], v[224:227], 0
	v_mfma_f32_16x16x32_bf16 v[12:15], v[128:131], v[232:235], 0
	v_mfma_f32_16x16x32_bf16 v[8:11], v[136:139], v[232:235], 0
	v_mfma_f32_16x16x32_bf16 v[60:63], v[132:135], v[194:197], v[60:63]
	v_mfma_f32_16x16x32_bf16 v[56:59], v[140:143], v[194:197], v[56:59]
	v_mfma_f32_16x16x32_bf16 v[40:43], v[140:143], v[218:221], v[40:43]
	v_mfma_f32_16x16x32_bf16 v[44:47], v[132:135], v[218:221], v[44:47]
	v_mfma_f32_16x16x32_bf16 v[28:31], v[132:135], v[228:231], v[28:31]
	v_mfma_f32_16x16x32_bf16 v[24:27], v[140:143], v[228:231], v[24:27]
	v_mfma_f32_16x16x32_bf16 v[8:11], v[140:143], v[236:239], v[8:11]
	v_mfma_f32_16x16x32_bf16 v[12:15], v[132:135], v[236:239], v[12:15]
	s_setprio 0
	s_setprio 1
	v_mfma_f32_16x16x32_bf16 v[52:55], v[144:147], v[190:193], 0
	v_mfma_f32_16x16x32_bf16 v[48:51], v[182:185], v[190:193], 0
	v_mfma_f32_16x16x32_bf16 v[36:39], v[144:147], v[214:217], 0
	v_mfma_f32_16x16x32_bf16 v[32:35], v[182:185], v[214:217], 0
	v_mfma_f32_16x16x32_bf16 v[20:23], v[144:147], v[224:227], 0
	v_mfma_f32_16x16x32_bf16 v[16:19], v[182:185], v[224:227], 0
	v_mfma_f32_16x16x32_bf16 v[4:7], v[144:147], v[232:235], 0
	v_mfma_f32_16x16x32_bf16 v[0:3], v[182:185], v[232:235], 0
	v_mfma_f32_16x16x32_bf16 v[52:55], v[148:151], v[194:197], v[52:55]
	v_mfma_f32_16x16x32_bf16 v[48:51], v[186:189], v[194:197], v[48:51]
	v_mfma_f32_16x16x32_bf16 v[32:35], v[186:189], v[218:221], v[32:35]
	v_mfma_f32_16x16x32_bf16 v[36:39], v[148:151], v[218:221], v[36:39]
	v_mfma_f32_16x16x32_bf16 v[20:23], v[148:151], v[228:231], v[20:23]
	v_mfma_f32_16x16x32_bf16 v[16:19], v[186:189], v[228:231], v[16:19]
	v_mfma_f32_16x16x32_bf16 v[0:3], v[186:189], v[236:239], v[0:3]
	v_mfma_f32_16x16x32_bf16 v[4:7], v[148:151], v[236:239], v[4:7]
	s_setprio 0
	s_barrier
	s_add_i32 s87, 0, 0x18000
	s_add_i32 s92, 0, 0x1c000
	v_add_u32_e32 v140, s87, v210
	v_add_u32_e32 v186, s92, v210
	ds_read_b128 v[128:131], v140
	ds_read_b128 v[132:135], v140 offset:1024
	ds_read_b128 v[136:139], v140 offset:2048
	ds_read_b128 v[140:143], v140 offset:3072
	ds_read_b128 v[144:147], v186
	ds_read_b128 v[148:151], v186 offset:1024
	ds_read_b128 v[182:185], v186 offset:2048
	ds_read_b128 v[186:189], v186 offset:3072
	s_add_u32 s60, s66, 0xb0000
	s_addc_u32 s61, s67, 0
	s_mov_b32 m0, s75
	v_lshl_add_u64 v[246:247], s[60:61], 0, v[176:177]
	ds_read_b128 v[190:193], v212 offset:32768
	ds_read_b128 v[194:197], v212 offset:33792
	ds_read_b128 v[214:217], v212 offset:34816
	ds_read_b128 v[218:221], v212 offset:35840
	ds_read_b128 v[224:227], v212 offset:36864
	ds_read_b128 v[228:231], v212 offset:37888
	ds_read_b128 v[232:235], v212 offset:38912
	ds_read_b128 v[236:239], v212 offset:39936
	global_load_lds_dwordx4 v[246:247], off
	v_lshl_add_u64 v[246:247], s[60:61], 0, v[174:175]
	s_mov_b32 m0, s76
	s_nop 0
	global_load_lds_dwordx4 v[246:247], off
	s_waitcnt vmcnt(8)
	s_waitcnt lgkmcnt(0)
	s_barrier
	s_setprio 1
	s_waitcnt lgkmcnt(0)
	v_mfma_f32_16x16x32_bf16 v[124:127], v[128:131], v[190:193], v[124:127]
	v_mfma_f32_16x16x32_bf16 v[120:123], v[136:139], v[190:193], v[120:123]
	v_mfma_f32_16x16x32_bf16 v[104:107], v[136:139], v[214:217], v[104:107]
	v_mfma_f32_16x16x32_bf16 v[108:111], v[128:131], v[214:217], v[108:111]
	v_mfma_f32_16x16x32_bf16 v[92:95], v[128:131], v[224:227], v[92:95]
	v_mfma_f32_16x16x32_bf16 v[88:91], v[136:139], v[224:227], v[88:91]
	v_mfma_f32_16x16x32_bf16 v[72:75], v[136:139], v[232:235], v[72:75]
	v_mfma_f32_16x16x32_bf16 v[76:79], v[128:131], v[232:235], v[76:79]
	v_mfma_f32_16x16x32_bf16 v[124:127], v[132:135], v[194:197], v[124:127]
	v_mfma_f32_16x16x32_bf16 v[120:123], v[140:143], v[194:197], v[120:123]
	v_mfma_f32_16x16x32_bf16 v[104:107], v[140:143], v[218:221], v[104:107]
	v_mfma_f32_16x16x32_bf16 v[108:111], v[132:135], v[218:221], v[108:111]
	v_mfma_f32_16x16x32_bf16 v[92:95], v[132:135], v[228:231], v[92:95]
	v_mfma_f32_16x16x32_bf16 v[88:91], v[140:143], v[228:231], v[88:91]
	v_mfma_f32_16x16x32_bf16 v[72:75], v[140:143], v[236:239], v[72:75]
	v_mfma_f32_16x16x32_bf16 v[76:79], v[132:135], v[236:239], v[76:79]
	s_setprio 0
	s_setprio 1
	v_mfma_f32_16x16x32_bf16 v[116:119], v[144:147], v[190:193], v[116:119]
	v_mfma_f32_16x16x32_bf16 v[112:115], v[182:185], v[190:193], v[112:115]
	v_mfma_f32_16x16x32_bf16 v[96:99], v[182:185], v[214:217], v[96:99]
	v_mfma_f32_16x16x32_bf16 v[100:103], v[144:147], v[214:217], v[100:103]
	v_mfma_f32_16x16x32_bf16 v[84:87], v[144:147], v[224:227], v[84:87]
	v_mfma_f32_16x16x32_bf16 v[80:83], v[182:185], v[224:227], v[80:83]
	v_mfma_f32_16x16x32_bf16 v[64:67], v[182:185], v[232:235], v[64:67]
	v_mfma_f32_16x16x32_bf16 v[68:71], v[144:147], v[232:235], v[68:71]
	v_mfma_f32_16x16x32_bf16 v[116:119], v[148:151], v[194:197], v[116:119]
	v_mfma_f32_16x16x32_bf16 v[112:115], v[186:189], v[194:197], v[112:115]
	v_mfma_f32_16x16x32_bf16 v[96:99], v[186:189], v[218:221], v[96:99]
	v_mfma_f32_16x16x32_bf16 v[100:103], v[148:151], v[218:221], v[100:103]
	v_mfma_f32_16x16x32_bf16 v[84:87], v[148:151], v[228:231], v[84:87]
	v_mfma_f32_16x16x32_bf16 v[80:83], v[186:189], v[228:231], v[80:83]
	v_mfma_f32_16x16x32_bf16 v[64:67], v[186:189], v[236:239], v[64:67]
	v_mfma_f32_16x16x32_bf16 v[68:71], v[148:151], v[236:239], v[68:71]
	s_setprio 0
	s_barrier
	s_add_i32 s60, s87, s68
	v_lshl_add_u64 v[198:199], v[198:199], 0, s[22:23]
	s_mov_b32 m0, s60
	ds_read_b128 v[190:193], v212 offset:49152
	ds_read_b128 v[194:197], v212 offset:50176
	ds_read_b128 v[214:217], v212 offset:51200
	ds_read_b128 v[218:221], v212 offset:52224
	ds_read_b128 v[224:227], v212 offset:53248
	ds_read_b128 v[228:231], v212 offset:54272
	ds_read_b128 v[232:235], v212 offset:55296
	ds_read_b128 v[236:239], v212 offset:56320
	global_load_lds_dwordx4 v[198:199], off
	s_add_i32 m0, s60, 0x2000
	s_add_u32 s18, s18, 0xb0080
	v_lshl_add_u64 v[198:199], v[240:241], 0, s[22:23]
	s_addc_u32 s19, s19, 0
	s_add_i32 s60, s92, s68
	global_load_lds_dwordx4 v[198:199], off
	v_lshl_add_u64 v[198:199], s[18:19], 0, v[152:153]
	s_mov_b32 m0, s60
	s_nop 0
	global_load_lds_dwordx4 v[198:199], off
	v_lshl_add_u64 v[198:199], s[18:19], 0, v[172:173]
	s_add_i32 m0, s60, 0x2000
	s_nop 0
	global_load_lds_dwordx4 v[198:199], off
	v_lshl_add_u64 v[198:199], v[242:243], 0, s[22:23]
	s_mov_b32 m0, s79
	s_nop 0
	global_load_lds_dwordx4 v[198:199], off
	v_lshl_add_u64 v[198:199], v[244:245], 0, s[22:23]
	s_mov_b32 m0, s80
	s_nop 0
	global_load_lds_dwordx4 v[198:199], off
	s_waitcnt vmcnt(8)
	s_waitcnt lgkmcnt(0)
	s_barrier
	s_setprio 1
	s_waitcnt lgkmcnt(0)
	v_mfma_f32_16x16x32_bf16 v[60:63], v[128:131], v[190:193], v[60:63]
	v_mfma_f32_16x16x32_bf16 v[56:59], v[136:139], v[190:193], v[56:59]
	v_mfma_f32_16x16x32_bf16 v[40:43], v[136:139], v[214:217], v[40:43]
	v_mfma_f32_16x16x32_bf16 v[44:47], v[128:131], v[214:217], v[44:47]
	v_mfma_f32_16x16x32_bf16 v[28:31], v[128:131], v[224:227], v[28:31]
	v_mfma_f32_16x16x32_bf16 v[24:27], v[136:139], v[224:227], v[24:27]
	v_mfma_f32_16x16x32_bf16 v[8:11], v[136:139], v[232:235], v[8:11]
	v_mfma_f32_16x16x32_bf16 v[12:15], v[128:131], v[232:235], v[12:15]
	v_mfma_f32_16x16x32_bf16 v[60:63], v[132:135], v[194:197], v[60:63]
	v_mfma_f32_16x16x32_bf16 v[56:59], v[140:143], v[194:197], v[56:59]
	v_mfma_f32_16x16x32_bf16 v[40:43], v[140:143], v[218:221], v[40:43]
	v_mfma_f32_16x16x32_bf16 v[44:47], v[132:135], v[218:221], v[44:47]
	v_mfma_f32_16x16x32_bf16 v[28:31], v[132:135], v[228:231], v[28:31]
	v_mfma_f32_16x16x32_bf16 v[24:27], v[140:143], v[228:231], v[24:27]
	v_mfma_f32_16x16x32_bf16 v[8:11], v[140:143], v[236:239], v[8:11]
	v_mfma_f32_16x16x32_bf16 v[12:15], v[132:135], v[236:239], v[12:15]
	s_setprio 0
	s_setprio 1
	v_mfma_f32_16x16x32_bf16 v[52:55], v[144:147], v[190:193], v[52:55]
	v_mfma_f32_16x16x32_bf16 v[48:51], v[182:185], v[190:193], v[48:51]
	v_mfma_f32_16x16x32_bf16 v[32:35], v[182:185], v[214:217], v[32:35]
	v_mfma_f32_16x16x32_bf16 v[36:39], v[144:147], v[214:217], v[36:39]
	v_mfma_f32_16x16x32_bf16 v[20:23], v[144:147], v[224:227], v[20:23]
	v_mfma_f32_16x16x32_bf16 v[16:19], v[182:185], v[224:227], v[16:19]
	v_mfma_f32_16x16x32_bf16 v[0:3], v[182:185], v[232:235], v[0:3]
	v_mfma_f32_16x16x32_bf16 v[4:7], v[144:147], v[232:235], v[4:7]
	v_mfma_f32_16x16x32_bf16 v[52:55], v[148:151], v[194:197], v[52:55]
	v_mfma_f32_16x16x32_bf16 v[48:51], v[186:189], v[194:197], v[48:51]
	v_mfma_f32_16x16x32_bf16 v[32:35], v[186:189], v[218:221], v[32:35]
	v_mfma_f32_16x16x32_bf16 v[36:39], v[148:151], v[218:221], v[36:39]
	v_mfma_f32_16x16x32_bf16 v[20:23], v[148:151], v[228:231], v[20:23]
	v_mfma_f32_16x16x32_bf16 v[16:19], v[186:189], v[228:231], v[16:19]
	v_mfma_f32_16x16x32_bf16 v[0:3], v[186:189], v[236:239], v[0:3]
	v_mfma_f32_16x16x32_bf16 v[4:7], v[148:151], v[236:239], v[4:7]
	s_setprio 0
	s_barrier
	s_add_i32 s86, s86, 2
	s_add_u32 s84, s84, 0x100
	s_addc_u32 s85, s85, 0
	s_cmp_gt_u32 s86, 41
	s_mov_b64 s[60:61], vcc
	.p2align	6

.LBB0_418:
	s_ashr_i32 s21, s20, 31
	s_lshl_b64 s[50:51], s[20:21], 19
	s_add_u32 s50, s26, s50
	s_addc_u32 s51, s27, s51
	s_and_b64 s[60:61], s[46:47], exec
	s_cselect_b32 s21, s51, s45
	s_cselect_b32 s78, s50, s44
	s_ashr_i32 s19, s18, 31
	s_lshl_b64 s[60:61], s[18:19], 19
	v_readlane_b32 s19, v254, 42
	s_add_u32 s60, s19, s60
	v_readlane_b32 s19, v254, 43
	s_addc_u32 s61, s19, s61
	s_and_b64 s[62:63], s[46:47], exec
	s_cselect_b32 s19, s61, s49
	s_cselect_b32 s79, s60, s48
	s_add_u32 s80, s48, 0x100
	s_addc_u32 s81, s49, 0
	s_add_u32 s48, s44, 0x40080
	s_addc_u32 s49, s45, 0
	s_mov_b32 s82, -2
	s_add_u32 s44, s48, 0xfffc0080
	s_addc_u32 s45, s49, -1
	s_cmp_eq_u32 s82, 12
	s_cselect_b32 s63, s21, s45
	s_cselect_b32 s62, s78, s44
	s_cselect_b32 s45, s19, s81
	s_cselect_b32 s44, s79, s80
	v_lshl_add_u64 v[182:183], s[48:49], 0, v[172:173]
	s_add_i32 m0, s59, 0xc000
	global_load_lds_dwordx4 v[182:183], off
	v_lshl_add_u64 v[182:183], s[48:49], 0, v[150:151]
	s_add_i32 m0, s59, 0xe000
	s_nop 0
	global_load_lds_dwordx4 v[182:183], off
	s_waitcnt vmcnt(8)
	s_waitcnt lgkmcnt(0)
	s_barrier
	s_setprio 1
	s_waitcnt lgkmcnt(0)
	v_mfma_f32_16x16x32_bf16 v[140:143], v[72:75], v[210:213], 0
	v_mfma_f32_16x16x32_bf16 v[136:139], v[80:83], v[210:213], 0
	v_mfma_f32_16x16x32_bf16 v[124:127], v[72:75], v[218:221], 0
	v_mfma_f32_16x16x32_bf16 v[120:123], v[80:83], v[218:221], 0
	v_mfma_f32_16x16x32_bf16 v[108:111], v[72:75], v[228:231], 0
	v_mfma_f32_16x16x32_bf16 v[104:107], v[80:83], v[228:231], 0
	v_mfma_f32_16x16x32_bf16 v[92:95], v[72:75], v[236:239], 0
	v_mfma_f32_16x16x32_bf16 v[84:87], v[80:83], v[236:239], 0
	v_mfma_f32_16x16x32_bf16 v[140:143], v[76:79], v[214:217], v[140:143]
	v_mfma_f32_16x16x32_bf16 v[136:139], v[88:91], v[214:217], v[136:139]
	v_mfma_f32_16x16x32_bf16 v[120:123], v[88:91], v[224:227], v[120:123]
	v_mfma_f32_16x16x32_bf16 v[124:127], v[76:79], v[224:227], v[124:127]
	v_mfma_f32_16x16x32_bf16 v[108:111], v[76:79], v[232:235], v[108:111]
	v_mfma_f32_16x16x32_bf16 v[104:107], v[88:91], v[232:235], v[104:107]
	v_mfma_f32_16x16x32_bf16 v[84:87], v[88:91], v[240:243], v[84:87]
	v_mfma_f32_16x16x32_bf16 v[92:95], v[76:79], v[240:243], v[92:95]
	s_setprio 0
	s_setprio 1
	v_mfma_f32_16x16x32_bf16 v[132:135], v[174:177], v[210:213], 0
	v_mfma_f32_16x16x32_bf16 v[128:131], v[190:193], v[210:213], 0
	v_mfma_f32_16x16x32_bf16 v[116:119], v[174:177], v[218:221], 0
	v_mfma_f32_16x16x32_bf16 v[112:115], v[190:193], v[218:221], 0
	v_mfma_f32_16x16x32_bf16 v[100:103], v[174:177], v[228:231], 0
	v_mfma_f32_16x16x32_bf16 v[96:99], v[190:193], v[228:231], 0
	v_mfma_f32_16x16x32_bf16 v[68:71], v[174:177], v[236:239], 0
	v_mfma_f32_16x16x32_bf16 v[64:67], v[190:193], v[236:239], 0
	v_mfma_f32_16x16x32_bf16 v[132:135], v[178:181], v[214:217], v[132:135]
	v_mfma_f32_16x16x32_bf16 v[128:131], v[194:197], v[214:217], v[128:131]
	v_mfma_f32_16x16x32_bf16 v[112:115], v[194:197], v[224:227], v[112:115]
	v_mfma_f32_16x16x32_bf16 v[116:119], v[178:181], v[224:227], v[116:119]
	v_mfma_f32_16x16x32_bf16 v[100:103], v[178:181], v[232:235], v[100:103]
	v_mfma_f32_16x16x32_bf16 v[96:99], v[194:197], v[232:235], v[96:99]
	v_mfma_f32_16x16x32_bf16 v[64:67], v[194:197], v[240:243], v[64:67]
	v_mfma_f32_16x16x32_bf16 v[68:71], v[178:181], v[240:243], v[68:71]
	s_setprio 0
	s_barrier
	s_add_i32 s83, s83, s8
	v_lshl_add_u64 v[182:183], s[44:45], 0, v[152:153]
	s_mov_b32 m0, s83
	ds_read_b128 v[210:213], v188 offset:16384
	ds_read_b128 v[214:217], v188 offset:17408
	ds_read_b128 v[218:221], v188 offset:18432
	ds_read_b128 v[224:227], v188 offset:19456
	ds_read_b128 v[228:231], v188 offset:20480
	ds_read_b128 v[232:235], v188 offset:21504
	ds_read_b128 v[236:239], v188 offset:22528
	ds_read_b128 v[240:243], v188 offset:23552
	global_load_lds_dwordx4 v[182:183], off
	s_add_i32 m0, s83, 0x2000
	s_add_u32 s84, s44, 0x40000
	v_lshl_add_u64 v[198:199], s[44:45], 0, v[144:145]
	s_addc_u32 s85, s45, 0
	s_add_i32 s83, s86, s8
	global_load_lds_dwordx4 v[198:199], off
	v_lshl_add_u64 v[244:245], s[84:85], 0, v[152:153]
	s_mov_b32 m0, s83
	v_lshl_add_u64 v[246:247], s[62:63], 0, v[146:147]
	global_load_lds_dwordx4 v[244:245], off
	v_lshl_add_u64 v[244:245], s[84:85], 0, v[144:145]
	s_add_i32 m0, s83, 0x2000
	s_nop 0
	global_load_lds_dwordx4 v[244:245], off
	v_lshl_add_u64 v[244:245], s[62:63], 0, v[148:149]
	s_mov_b32 m0, s59
	s_nop 0
	global_load_lds_dwordx4 v[244:245], off
	s_mov_b32 m0, s66
	s_nop 0
	global_load_lds_dwordx4 v[246:247], off
	s_waitcnt vmcnt(8)
	s_waitcnt lgkmcnt(0)
	s_barrier
	s_setprio 1
	s_waitcnt lgkmcnt(0)
	v_mfma_f32_16x16x32_bf16 v[60:63], v[72:75], v[210:213], 0
	v_mfma_f32_16x16x32_bf16 v[56:59], v[80:83], v[210:213], 0
	v_mfma_f32_16x16x32_bf16 v[44:47], v[72:75], v[218:221], 0
	v_mfma_f32_16x16x32_bf16 v[40:43], v[80:83], v[218:221], 0
	v_mfma_f32_16x16x32_bf16 v[28:31], v[72:75], v[228:231], 0
	v_mfma_f32_16x16x32_bf16 v[24:27], v[80:83], v[228:231], 0
	v_mfma_f32_16x16x32_bf16 v[12:15], v[72:75], v[236:239], 0
	v_mfma_f32_16x16x32_bf16 v[8:11], v[80:83], v[236:239], 0
	v_mfma_f32_16x16x32_bf16 v[60:63], v[76:79], v[214:217], v[60:63]
	v_mfma_f32_16x16x32_bf16 v[56:59], v[88:91], v[214:217], v[56:59]
	v_mfma_f32_16x16x32_bf16 v[40:43], v[88:91], v[224:227], v[40:43]
	v_mfma_f32_16x16x32_bf16 v[44:47], v[76:79], v[224:227], v[44:47]
	v_mfma_f32_16x16x32_bf16 v[28:31], v[76:79], v[232:235], v[28:31]
	v_mfma_f32_16x16x32_bf16 v[24:27], v[88:91], v[232:235], v[24:27]
	v_mfma_f32_16x16x32_bf16 v[8:11], v[88:91], v[240:243], v[8:11]
	v_mfma_f32_16x16x32_bf16 v[12:15], v[76:79], v[240:243], v[12:15]
	s_setprio 0
	s_setprio 1
	v_mfma_f32_16x16x32_bf16 v[52:55], v[174:177], v[210:213], 0
	v_mfma_f32_16x16x32_bf16 v[48:51], v[190:193], v[210:213], 0
	v_mfma_f32_16x16x32_bf16 v[36:39], v[174:177], v[218:221], 0
	v_mfma_f32_16x16x32_bf16 v[32:35], v[190:193], v[218:221], 0
	v_mfma_f32_16x16x32_bf16 v[20:23], v[174:177], v[228:231], 0
	v_mfma_f32_16x16x32_bf16 v[16:19], v[190:193], v[228:231], 0
	v_mfma_f32_16x16x32_bf16 v[4:7], v[174:177], v[236:239], 0
	v_mfma_f32_16x16x32_bf16 v[0:3], v[190:193], v[236:239], 0
	v_mfma_f32_16x16x32_bf16 v[52:55], v[178:181], v[214:217], v[52:55]
	v_mfma_f32_16x16x32_bf16 v[48:51], v[194:197], v[214:217], v[48:51]
	v_mfma_f32_16x16x32_bf16 v[32:35], v[194:197], v[224:227], v[32:35]
	v_mfma_f32_16x16x32_bf16 v[36:39], v[178:181], v[224:227], v[36:39]
	v_mfma_f32_16x16x32_bf16 v[20:23], v[178:181], v[232:235], v[20:23]
	v_mfma_f32_16x16x32_bf16 v[16:19], v[194:197], v[232:235], v[16:19]
	v_mfma_f32_16x16x32_bf16 v[0:3], v[194:197], v[240:243], v[0:3]
	v_mfma_f32_16x16x32_bf16 v[4:7], v[178:181], v[240:243], v[4:7]
	s_setprio 0
	s_barrier
	s_add_i32 s83, 0, 0x18000
	s_add_i32 s84, 0, 0x1c000
	v_add_u32_e32 v88, s83, v185
	v_add_u32_e32 v189, s84, v185
	ds_read_b128 v[72:75], v88
	ds_read_b128 v[76:79], v88 offset:1024
	ds_read_b128 v[80:83], v88 offset:2048
	ds_read_b128 v[88:91], v88 offset:3072
	ds_read_b128 v[174:177], v189
	ds_read_b128 v[178:181], v189 offset:1024
	ds_read_b128 v[190:193], v189 offset:2048
	ds_read_b128 v[194:197], v189 offset:3072
	s_add_u32 s62, s62, 0x40000
	s_addc_u32 s63, s63, 0
	s_mov_b32 m0, s67
	v_lshl_add_u64 v[248:249], s[62:63], 0, v[148:149]
	ds_read_b128 v[210:213], v188 offset:32768
	ds_read_b128 v[214:217], v188 offset:33792
	ds_read_b128 v[218:221], v188 offset:34816
	ds_read_b128 v[224:227], v188 offset:35840
	ds_read_b128 v[228:231], v188 offset:36864
	ds_read_b128 v[232:235], v188 offset:37888
	ds_read_b128 v[236:239], v188 offset:38912
	ds_read_b128 v[240:243], v188 offset:39936
	global_load_lds_dwordx4 v[248:249], off
	v_lshl_add_u64 v[248:249], s[62:63], 0, v[146:147]
	s_mov_b32 m0, s68
	s_nop 0
	global_load_lds_dwordx4 v[248:249], off
	s_waitcnt vmcnt(8)
	s_waitcnt lgkmcnt(0)
	s_barrier
	s_setprio 1
	s_waitcnt lgkmcnt(0)
	v_mfma_f32_16x16x32_bf16 v[140:143], v[72:75], v[210:213], v[140:143]
	v_mfma_f32_16x16x32_bf16 v[136:139], v[80:83], v[210:213], v[136:139]
	v_mfma_f32_16x16x32_bf16 v[120:123], v[80:83], v[218:221], v[120:123]
	v_mfma_f32_16x16x32_bf16 v[124:127], v[72:75], v[218:221], v[124:127]
	v_mfma_f32_16x16x32_bf16 v[108:111], v[72:75], v[228:231], v[108:111]
	v_mfma_f32_16x16x32_bf16 v[104:107], v[80:83], v[228:231], v[104:107]
	v_mfma_f32_16x16x32_bf16 v[84:87], v[80:83], v[236:239], v[84:87]
	v_mfma_f32_16x16x32_bf16 v[92:95], v[72:75], v[236:239], v[92:95]
	v_mfma_f32_16x16x32_bf16 v[140:143], v[76:79], v[214:217], v[140:143]
	v_mfma_f32_16x16x32_bf16 v[136:139], v[88:91], v[214:217], v[136:139]
	v_mfma_f32_16x16x32_bf16 v[120:123], v[88:91], v[224:227], v[120:123]
	v_mfma_f32_16x16x32_bf16 v[124:127], v[76:79], v[224:227], v[124:127]
	v_mfma_f32_16x16x32_bf16 v[108:111], v[76:79], v[232:235], v[108:111]
	v_mfma_f32_16x16x32_bf16 v[104:107], v[88:91], v[232:235], v[104:107]
	v_mfma_f32_16x16x32_bf16 v[84:87], v[88:91], v[240:243], v[84:87]
	v_mfma_f32_16x16x32_bf16 v[92:95], v[76:79], v[240:243], v[92:95]
	s_setprio 0
	s_setprio 1
	v_mfma_f32_16x16x32_bf16 v[132:135], v[174:177], v[210:213], v[132:135]
	v_mfma_f32_16x16x32_bf16 v[128:131], v[190:193], v[210:213], v[128:131]
	v_mfma_f32_16x16x32_bf16 v[112:115], v[190:193], v[218:221], v[112:115]
	v_mfma_f32_16x16x32_bf16 v[116:119], v[174:177], v[218:221], v[116:119]
	v_mfma_f32_16x16x32_bf16 v[100:103], v[174:177], v[228:231], v[100:103]
	v_mfma_f32_16x16x32_bf16 v[96:99], v[190:193], v[228:231], v[96:99]
	v_mfma_f32_16x16x32_bf16 v[64:67], v[190:193], v[236:239], v[64:67]
	v_mfma_f32_16x16x32_bf16 v[68:71], v[174:177], v[236:239], v[68:71]
	v_mfma_f32_16x16x32_bf16 v[132:135], v[178:181], v[214:217], v[132:135]
	v_mfma_f32_16x16x32_bf16 v[128:131], v[194:197], v[214:217], v[128:131]
	v_mfma_f32_16x16x32_bf16 v[112:115], v[194:197], v[224:227], v[112:115]
	v_mfma_f32_16x16x32_bf16 v[116:119], v[178:181], v[224:227], v[116:119]
	v_mfma_f32_16x16x32_bf16 v[100:103], v[178:181], v[232:235], v[100:103]
	v_mfma_f32_16x16x32_bf16 v[96:99], v[194:197], v[232:235], v[96:99]
	v_mfma_f32_16x16x32_bf16 v[64:67], v[194:197], v[240:243], v[64:67]
	v_mfma_f32_16x16x32_bf16 v[68:71], v[178:181], v[240:243], v[68:71]
	s_setprio 0
	s_barrier
	s_add_i32 s62, s83, s8
	v_lshl_add_u64 v[182:183], v[182:183], 0, s[22:23]
	s_mov_b32 m0, s62
	ds_read_b128 v[210:213], v188 offset:49152
	ds_read_b128 v[214:217], v188 offset:50176
	ds_read_b128 v[218:221], v188 offset:51200
	ds_read_b128 v[224:227], v188 offset:52224
	ds_read_b128 v[228:231], v188 offset:53248
	ds_read_b128 v[232:235], v188 offset:54272
	ds_read_b128 v[236:239], v188 offset:55296
	ds_read_b128 v[240:243], v188 offset:56320
	global_load_lds_dwordx4 v[182:183], off
	s_add_i32 m0, s62, 0x2000
	s_add_u32 s44, s44, 0x40080
	v_lshl_add_u64 v[182:183], v[198:199], 0, s[22:23]
	s_addc_u32 s45, s45, 0
	s_add_i32 s62, s84, s8
	global_load_lds_dwordx4 v[182:183], off
	v_lshl_add_u64 v[182:183], s[44:45], 0, v[152:153]
	s_mov_b32 m0, s62
	s_nop 0
	global_load_lds_dwordx4 v[182:183], off
	v_lshl_add_u64 v[182:183], s[44:45], 0, v[144:145]
	s_add_i32 m0, s62, 0x2000
	s_nop 0
	global_load_lds_dwordx4 v[182:183], off
	v_lshl_add_u64 v[182:183], v[244:245], 0, s[22:23]
	s_mov_b32 m0, s69
	s_nop 0
	global_load_lds_dwordx4 v[182:183], off
	v_lshl_add_u64 v[182:183], v[246:247], 0, s[22:23]
	s_mov_b32 m0, s74
	s_nop 0
	global_load_lds_dwordx4 v[182:183], off
	s_waitcnt vmcnt(8)
	s_waitcnt lgkmcnt(0)
	s_barrier
	s_setprio 1
	s_waitcnt lgkmcnt(0)
	v_mfma_f32_16x16x32_bf16 v[60:63], v[72:75], v[210:213], v[60:63]
	v_mfma_f32_16x16x32_bf16 v[56:59], v[80:83], v[210:213], v[56:59]
	v_mfma_f32_16x16x32_bf16 v[40:43], v[80:83], v[218:221], v[40:43]
	v_mfma_f32_16x16x32_bf16 v[44:47], v[72:75], v[218:221], v[44:47]
	v_mfma_f32_16x16x32_bf16 v[28:31], v[72:75], v[228:231], v[28:31]
	v_mfma_f32_16x16x32_bf16 v[24:27], v[80:83], v[228:231], v[24:27]
	v_mfma_f32_16x16x32_bf16 v[8:11], v[80:83], v[236:239], v[8:11]
	v_mfma_f32_16x16x32_bf16 v[12:15], v[72:75], v[236:239], v[12:15]
	v_mfma_f32_16x16x32_bf16 v[60:63], v[76:79], v[214:217], v[60:63]
	v_mfma_f32_16x16x32_bf16 v[56:59], v[88:91], v[214:217], v[56:59]
	v_mfma_f32_16x16x32_bf16 v[40:43], v[88:91], v[224:227], v[40:43]
	v_mfma_f32_16x16x32_bf16 v[44:47], v[76:79], v[224:227], v[44:47]
	v_mfma_f32_16x16x32_bf16 v[28:31], v[76:79], v[232:235], v[28:31]
	v_mfma_f32_16x16x32_bf16 v[24:27], v[88:91], v[232:235], v[24:27]
	v_mfma_f32_16x16x32_bf16 v[8:11], v[88:91], v[240:243], v[8:11]
	v_mfma_f32_16x16x32_bf16 v[12:15], v[76:79], v[240:243], v[12:15]
	s_setprio 0
	s_setprio 1
	v_mfma_f32_16x16x32_bf16 v[52:55], v[174:177], v[210:213], v[52:55]
	v_mfma_f32_16x16x32_bf16 v[48:51], v[190:193], v[210:213], v[48:51]
	v_mfma_f32_16x16x32_bf16 v[32:35], v[190:193], v[218:221], v[32:35]
	v_mfma_f32_16x16x32_bf16 v[36:39], v[174:177], v[218:221], v[36:39]
	v_mfma_f32_16x16x32_bf16 v[20:23], v[174:177], v[228:231], v[20:23]
	v_mfma_f32_16x16x32_bf16 v[16:19], v[190:193], v[228:231], v[16:19]
	v_mfma_f32_16x16x32_bf16 v[0:3], v[190:193], v[236:239], v[0:3]
	v_mfma_f32_16x16x32_bf16 v[4:7], v[174:177], v[236:239], v[4:7]
	v_mfma_f32_16x16x32_bf16 v[52:55], v[178:181], v[214:217], v[52:55]
	v_mfma_f32_16x16x32_bf16 v[48:51], v[194:197], v[214:217], v[48:51]
	v_mfma_f32_16x16x32_bf16 v[32:35], v[194:197], v[224:227], v[32:35]
	v_mfma_f32_16x16x32_bf16 v[36:39], v[178:181], v[224:227], v[36:39]
	v_mfma_f32_16x16x32_bf16 v[20:23], v[178:181], v[232:235], v[20:23]
	v_mfma_f32_16x16x32_bf16 v[16:19], v[194:197], v[232:235], v[16:19]
	v_mfma_f32_16x16x32_bf16 v[0:3], v[194:197], v[240:243], v[0:3]
	v_mfma_f32_16x16x32_bf16 v[4:7], v[178:181], v[240:243], v[4:7]
	s_setprio 0
	s_barrier
	s_add_i32 s82, s82, 2
	s_add_u32 s80, s80, 0x100
	s_addc_u32 s81, s81, 0
	s_add_u32 s48, s48, 0x100
	s_addc_u32 s49, s49, 0
	s_cmp_gt_u32 s82, 13
	.p2align	6

.LBB0_704:
	s_ashr_i32 s21, s20, 31
	s_lshl_b64 s[48:49], s[20:21], 18
	v_readlane_b32 s19, v254, 14
	s_add_u32 s48, s19, s48
	v_readlane_b32 s19, v254, 15
	s_addc_u32 s49, s19, s49
	s_and_b64 s[50:51], s[46:47], exec
	s_cselect_b32 s21, s49, s45
	s_cselect_b32 s78, s48, s44
	s_ashr_i32 s19, s18, 31
	s_lshl_b64 s[50:51], s[18:19], 18
	v_readlane_b32 s19, v254, 10
	s_add_u32 s50, s19, s50
	v_readlane_b32 s19, v254, 11
	s_addc_u32 s51, s19, s51
	s_and_b64 s[62:63], s[46:47], exec
	s_cselect_b32 s19, s51, s61
	s_cselect_b32 s79, s50, s60
	s_add_u32 s80, s60, 0x100
	s_addc_u32 s81, s61, 0
	s_add_u32 s60, s44, 0x20080
	s_addc_u32 s61, s45, 0
	s_mov_b32 s82, -2
	s_add_u32 s44, s60, 0xfffe0080
	s_addc_u32 s45, s61, -1
	s_cmp_eq_u32 s82, 4
	s_cselect_b32 s63, s21, s45
	s_cselect_b32 s62, s78, s44
	s_cselect_b32 s45, s19, s81
	s_cselect_b32 s44, s79, s80
	v_lshl_add_u64 v[198:199], s[60:61], 0, v[180:181]
	s_add_i32 m0, s59, 0xc000
	global_load_lds_dwordx4 v[198:199], off
	v_lshl_add_u64 v[198:199], s[60:61], 0, v[178:179]
	s_add_i32 m0, s59, 0xe000
	s_nop 0
	global_load_lds_dwordx4 v[198:199], off
	s_waitcnt vmcnt(8)
	s_waitcnt lgkmcnt(0)
	s_barrier
	s_setprio 1
	s_waitcnt lgkmcnt(0)
	v_mfma_f32_16x16x32_bf16 v[128:131], v[124:127], v[190:193], 0
	v_mfma_f32_16x16x32_bf16 v[120:123], v[136:139], v[190:193], 0
	v_mfma_f32_16x16x32_bf16 v[108:111], v[124:127], v[214:217], 0
	v_mfma_f32_16x16x32_bf16 v[104:107], v[136:139], v[214:217], 0
	v_mfma_f32_16x16x32_bf16 v[92:95], v[124:127], v[224:227], 0
	v_mfma_f32_16x16x32_bf16 v[88:91], v[136:139], v[224:227], 0
	v_mfma_f32_16x16x32_bf16 v[76:79], v[124:127], v[232:235], 0
	v_mfma_f32_16x16x32_bf16 v[72:75], v[136:139], v[232:235], 0
	v_mfma_f32_16x16x32_bf16 v[128:131], v[132:135], v[210:213], v[128:131]
	v_mfma_f32_16x16x32_bf16 v[120:123], v[140:143], v[210:213], v[120:123]
	v_mfma_f32_16x16x32_bf16 v[104:107], v[140:143], v[218:221], v[104:107]
	v_mfma_f32_16x16x32_bf16 v[108:111], v[132:135], v[218:221], v[108:111]
	v_mfma_f32_16x16x32_bf16 v[92:95], v[132:135], v[228:231], v[92:95]
	v_mfma_f32_16x16x32_bf16 v[88:91], v[140:143], v[228:231], v[88:91]
	v_mfma_f32_16x16x32_bf16 v[72:75], v[140:143], v[236:239], v[72:75]
	v_mfma_f32_16x16x32_bf16 v[76:79], v[132:135], v[236:239], v[76:79]
	s_setprio 0
	s_setprio 1
	v_mfma_f32_16x16x32_bf16 v[116:119], v[144:147], v[190:193], 0
	v_mfma_f32_16x16x32_bf16 v[112:115], v[182:185], v[190:193], 0
	v_mfma_f32_16x16x32_bf16 v[100:103], v[144:147], v[214:217], 0
	v_mfma_f32_16x16x32_bf16 v[96:99], v[182:185], v[214:217], 0
	v_mfma_f32_16x16x32_bf16 v[84:87], v[144:147], v[224:227], 0
	v_mfma_f32_16x16x32_bf16 v[80:83], v[182:185], v[224:227], 0
	v_mfma_f32_16x16x32_bf16 v[68:71], v[144:147], v[232:235], 0
	v_mfma_f32_16x16x32_bf16 v[64:67], v[182:185], v[232:235], 0
	v_mfma_f32_16x16x32_bf16 v[116:119], v[148:151], v[210:213], v[116:119]
	v_mfma_f32_16x16x32_bf16 v[112:115], v[186:189], v[210:213], v[112:115]
	v_mfma_f32_16x16x32_bf16 v[96:99], v[186:189], v[218:221], v[96:99]
	v_mfma_f32_16x16x32_bf16 v[100:103], v[148:151], v[218:221], v[100:103]
	v_mfma_f32_16x16x32_bf16 v[84:87], v[148:151], v[228:231], v[84:87]
	v_mfma_f32_16x16x32_bf16 v[80:83], v[186:189], v[228:231], v[80:83]
	v_mfma_f32_16x16x32_bf16 v[64:67], v[186:189], v[236:239], v[64:67]
	v_mfma_f32_16x16x32_bf16 v[68:71], v[148:151], v[236:239], v[68:71]
	s_setprio 0
	s_barrier
	s_add_i32 s83, s83, s8
	v_lshl_add_u64 v[198:199], s[44:45], 0, v[152:153]
	s_mov_b32 m0, s83
	ds_read_b128 v[190:193], v197 offset:16384
	ds_read_b128 v[210:213], v197 offset:17408
	ds_read_b128 v[214:217], v197 offset:18432
	ds_read_b128 v[218:221], v197 offset:19456
	ds_read_b128 v[224:227], v197 offset:20480
	ds_read_b128 v[228:231], v197 offset:21504
	ds_read_b128 v[232:235], v197 offset:22528
	ds_read_b128 v[236:239], v197 offset:23552
	global_load_lds_dwordx4 v[198:199], off
	s_add_i32 m0, s83, 0x2000
	s_add_u32 s84, s44, 0x20000
	v_lshl_add_u64 v[240:241], s[44:45], 0, v[172:173]
	s_addc_u32 s85, s45, 0
	s_add_i32 s83, s86, s8
	global_load_lds_dwordx4 v[240:241], off
	v_lshl_add_u64 v[242:243], s[84:85], 0, v[152:153]
	s_mov_b32 m0, s83
	v_lshl_add_u64 v[244:245], s[62:63], 0, v[174:175]
	global_load_lds_dwordx4 v[242:243], off
	v_lshl_add_u64 v[242:243], s[84:85], 0, v[172:173]
	s_add_i32 m0, s83, 0x2000
	s_nop 0
	global_load_lds_dwordx4 v[242:243], off
	v_lshl_add_u64 v[242:243], s[62:63], 0, v[176:177]
	s_mov_b32 m0, s59
	s_nop 0
	global_load_lds_dwordx4 v[242:243], off
	s_mov_b32 m0, s66
	s_nop 0
	global_load_lds_dwordx4 v[244:245], off
	s_waitcnt vmcnt(8)
	s_waitcnt lgkmcnt(0)
	s_barrier
	s_setprio 1
	s_waitcnt lgkmcnt(0)
	v_mfma_f32_16x16x32_bf16 v[60:63], v[124:127], v[190:193], 0
	v_mfma_f32_16x16x32_bf16 v[56:59], v[136:139], v[190:193], 0
	v_mfma_f32_16x16x32_bf16 v[48:51], v[124:127], v[214:217], 0
	v_mfma_f32_16x16x32_bf16 v[40:43], v[136:139], v[214:217], 0
	v_mfma_f32_16x16x32_bf16 v[32:35], v[124:127], v[224:227], 0
	v_mfma_f32_16x16x32_bf16 v[24:27], v[136:139], v[224:227], 0
	v_mfma_f32_16x16x32_bf16 v[16:19], v[124:127], v[232:235], 0
	v_mfma_f32_16x16x32_bf16 v[8:11], v[136:139], v[232:235], 0
	v_mfma_f32_16x16x32_bf16 v[60:63], v[132:135], v[210:213], v[60:63]
	v_mfma_f32_16x16x32_bf16 v[56:59], v[140:143], v[210:213], v[56:59]
	v_mfma_f32_16x16x32_bf16 v[40:43], v[140:143], v[218:221], v[40:43]
	v_mfma_f32_16x16x32_bf16 v[48:51], v[132:135], v[218:221], v[48:51]
	v_mfma_f32_16x16x32_bf16 v[32:35], v[132:135], v[228:231], v[32:35]
	v_mfma_f32_16x16x32_bf16 v[24:27], v[140:143], v[228:231], v[24:27]
	v_mfma_f32_16x16x32_bf16 v[8:11], v[140:143], v[236:239], v[8:11]
	v_mfma_f32_16x16x32_bf16 v[16:19], v[132:135], v[236:239], v[16:19]
	s_setprio 0
	s_setprio 1
	v_mfma_f32_16x16x32_bf16 v[52:55], v[144:147], v[190:193], 0
	v_mfma_f32_16x16x32_bf16 v[44:47], v[182:185], v[190:193], 0
	v_mfma_f32_16x16x32_bf16 v[36:39], v[144:147], v[214:217], 0
	v_mfma_f32_16x16x32_bf16 v[28:31], v[182:185], v[214:217], 0
	v_mfma_f32_16x16x32_bf16 v[20:23], v[144:147], v[224:227], 0
	v_mfma_f32_16x16x32_bf16 v[12:15], v[182:185], v[224:227], 0
	v_mfma_f32_16x16x32_bf16 v[4:7], v[144:147], v[232:235], 0
	v_mfma_f32_16x16x32_bf16 v[0:3], v[182:185], v[232:235], 0
	v_mfma_f32_16x16x32_bf16 v[52:55], v[148:151], v[210:213], v[52:55]
	v_mfma_f32_16x16x32_bf16 v[44:47], v[186:189], v[210:213], v[44:47]
	v_mfma_f32_16x16x32_bf16 v[28:31], v[186:189], v[218:221], v[28:31]
	v_mfma_f32_16x16x32_bf16 v[36:39], v[148:151], v[218:221], v[36:39]
	v_mfma_f32_16x16x32_bf16 v[20:23], v[148:151], v[228:231], v[20:23]
	v_mfma_f32_16x16x32_bf16 v[12:15], v[186:189], v[228:231], v[12:15]
	v_mfma_f32_16x16x32_bf16 v[0:3], v[186:189], v[236:239], v[0:3]
	v_mfma_f32_16x16x32_bf16 v[4:7], v[148:151], v[236:239], v[4:7]
	s_setprio 0
	s_barrier
	s_add_i32 s83, 0, 0x18000
	s_add_i32 s84, 0, 0x1c000
	v_add_u32_e32 v140, s83, v195
	v_add_u32_e32 v186, s84, v195
	ds_read_b128 v[124:127], v140
	ds_read_b128 v[132:135], v140 offset:1024
	ds_read_b128 v[136:139], v140 offset:2048
	ds_read_b128 v[140:143], v140 offset:3072
	ds_read_b128 v[144:147], v186
	ds_read_b128 v[148:151], v186 offset:1024
	ds_read_b128 v[182:185], v186 offset:2048
	ds_read_b128 v[186:189], v186 offset:3072
	s_add_u32 s62, s62, 0x20000
	s_addc_u32 s63, s63, 0
	s_mov_b32 m0, s67
	v_lshl_add_u64 v[246:247], s[62:63], 0, v[176:177]
	ds_read_b128 v[190:193], v197 offset:32768
	ds_read_b128 v[210:213], v197 offset:33792
	ds_read_b128 v[214:217], v197 offset:34816
	ds_read_b128 v[218:221], v197 offset:35840
	ds_read_b128 v[224:227], v197 offset:36864
	ds_read_b128 v[228:231], v197 offset:37888
	ds_read_b128 v[232:235], v197 offset:38912
	ds_read_b128 v[236:239], v197 offset:39936
	global_load_lds_dwordx4 v[246:247], off
	v_lshl_add_u64 v[246:247], s[62:63], 0, v[174:175]
	s_mov_b32 m0, s68
	s_nop 0
	global_load_lds_dwordx4 v[246:247], off
	s_waitcnt vmcnt(8)
	s_waitcnt lgkmcnt(0)
	s_barrier
	s_setprio 1
	s_waitcnt lgkmcnt(0)
	v_mfma_f32_16x16x32_bf16 v[128:131], v[124:127], v[190:193], v[128:131]
	v_mfma_f32_16x16x32_bf16 v[120:123], v[136:139], v[190:193], v[120:123]
	v_mfma_f32_16x16x32_bf16 v[104:107], v[136:139], v[214:217], v[104:107]
	v_mfma_f32_16x16x32_bf16 v[108:111], v[124:127], v[214:217], v[108:111]
	v_mfma_f32_16x16x32_bf16 v[92:95], v[124:127], v[224:227], v[92:95]
	v_mfma_f32_16x16x32_bf16 v[88:91], v[136:139], v[224:227], v[88:91]
	v_mfma_f32_16x16x32_bf16 v[72:75], v[136:139], v[232:235], v[72:75]
	v_mfma_f32_16x16x32_bf16 v[76:79], v[124:127], v[232:235], v[76:79]
	v_mfma_f32_16x16x32_bf16 v[128:131], v[132:135], v[210:213], v[128:131]
	v_mfma_f32_16x16x32_bf16 v[120:123], v[140:143], v[210:213], v[120:123]
	v_mfma_f32_16x16x32_bf16 v[104:107], v[140:143], v[218:221], v[104:107]
	v_mfma_f32_16x16x32_bf16 v[108:111], v[132:135], v[218:221], v[108:111]
	v_mfma_f32_16x16x32_bf16 v[92:95], v[132:135], v[228:231], v[92:95]
	v_mfma_f32_16x16x32_bf16 v[88:91], v[140:143], v[228:231], v[88:91]
	v_mfma_f32_16x16x32_bf16 v[72:75], v[140:143], v[236:239], v[72:75]
	v_mfma_f32_16x16x32_bf16 v[76:79], v[132:135], v[236:239], v[76:79]
	s_setprio 0
	s_setprio 1
	v_mfma_f32_16x16x32_bf16 v[116:119], v[144:147], v[190:193], v[116:119]
	v_mfma_f32_16x16x32_bf16 v[112:115], v[182:185], v[190:193], v[112:115]
	v_mfma_f32_16x16x32_bf16 v[96:99], v[182:185], v[214:217], v[96:99]
	v_mfma_f32_16x16x32_bf16 v[100:103], v[144:147], v[214:217], v[100:103]
	v_mfma_f32_16x16x32_bf16 v[84:87], v[144:147], v[224:227], v[84:87]
	v_mfma_f32_16x16x32_bf16 v[80:83], v[182:185], v[224:227], v[80:83]
	v_mfma_f32_16x16x32_bf16 v[64:67], v[182:185], v[232:235], v[64:67]
	v_mfma_f32_16x16x32_bf16 v[68:71], v[144:147], v[232:235], v[68:71]
	v_mfma_f32_16x16x32_bf16 v[116:119], v[148:151], v[210:213], v[116:119]
	v_mfma_f32_16x16x32_bf16 v[112:115], v[186:189], v[210:213], v[112:115]
	v_mfma_f32_16x16x32_bf16 v[96:99], v[186:189], v[218:221], v[96:99]
	v_mfma_f32_16x16x32_bf16 v[100:103], v[148:151], v[218:221], v[100:103]
	v_mfma_f32_16x16x32_bf16 v[84:87], v[148:151], v[228:231], v[84:87]
	v_mfma_f32_16x16x32_bf16 v[80:83], v[186:189], v[228:231], v[80:83]
	v_mfma_f32_16x16x32_bf16 v[64:67], v[186:189], v[236:239], v[64:67]
	v_mfma_f32_16x16x32_bf16 v[68:71], v[148:151], v[236:239], v[68:71]
	s_setprio 0
	s_barrier
	s_add_i32 s62, s83, s8
	v_lshl_add_u64 v[198:199], v[198:199], 0, s[22:23]
	s_mov_b32 m0, s62
	ds_read_b128 v[190:193], v197 offset:49152
	ds_read_b128 v[210:213], v197 offset:50176
	ds_read_b128 v[214:217], v197 offset:51200
	ds_read_b128 v[218:221], v197 offset:52224
	ds_read_b128 v[224:227], v197 offset:53248
	ds_read_b128 v[228:231], v197 offset:54272
	ds_read_b128 v[232:235], v197 offset:55296
	ds_read_b128 v[236:239], v197 offset:56320
	global_load_lds_dwordx4 v[198:199], off
	s_add_i32 m0, s62, 0x2000
	s_add_u32 s44, s44, 0x20080
	v_lshl_add_u64 v[198:199], v[240:241], 0, s[22:23]
	s_addc_u32 s45, s45, 0
	s_add_i32 s62, s84, s8
	global_load_lds_dwordx4 v[198:199], off
	v_lshl_add_u64 v[198:199], s[44:45], 0, v[152:153]
	s_mov_b32 m0, s62
	s_nop 0
	global_load_lds_dwordx4 v[198:199], off
	v_lshl_add_u64 v[198:199], s[44:45], 0, v[172:173]
	s_add_i32 m0, s62, 0x2000
	s_nop 0
	global_load_lds_dwordx4 v[198:199], off
	v_lshl_add_u64 v[198:199], v[242:243], 0, s[22:23]
	s_mov_b32 m0, s69
	s_nop 0
	global_load_lds_dwordx4 v[198:199], off
	v_lshl_add_u64 v[198:199], v[244:245], 0, s[22:23]
	s_mov_b32 m0, s74
	s_nop 0
	global_load_lds_dwordx4 v[198:199], off
	s_waitcnt vmcnt(8)
	s_waitcnt lgkmcnt(0)
	s_barrier
	s_setprio 1
	s_waitcnt lgkmcnt(0)
	v_mfma_f32_16x16x32_bf16 v[60:63], v[124:127], v[190:193], v[60:63]
	v_mfma_f32_16x16x32_bf16 v[56:59], v[136:139], v[190:193], v[56:59]
	v_mfma_f32_16x16x32_bf16 v[40:43], v[136:139], v[214:217], v[40:43]
	v_mfma_f32_16x16x32_bf16 v[48:51], v[124:127], v[214:217], v[48:51]
	v_mfma_f32_16x16x32_bf16 v[32:35], v[124:127], v[224:227], v[32:35]
	v_mfma_f32_16x16x32_bf16 v[24:27], v[136:139], v[224:227], v[24:27]
	v_mfma_f32_16x16x32_bf16 v[8:11], v[136:139], v[232:235], v[8:11]
	v_mfma_f32_16x16x32_bf16 v[16:19], v[124:127], v[232:235], v[16:19]
	v_mfma_f32_16x16x32_bf16 v[60:63], v[132:135], v[210:213], v[60:63]
	v_mfma_f32_16x16x32_bf16 v[56:59], v[140:143], v[210:213], v[56:59]
	v_mfma_f32_16x16x32_bf16 v[40:43], v[140:143], v[218:221], v[40:43]
	v_mfma_f32_16x16x32_bf16 v[48:51], v[132:135], v[218:221], v[48:51]
	v_mfma_f32_16x16x32_bf16 v[32:35], v[132:135], v[228:231], v[32:35]
	v_mfma_f32_16x16x32_bf16 v[24:27], v[140:143], v[228:231], v[24:27]
	v_mfma_f32_16x16x32_bf16 v[8:11], v[140:143], v[236:239], v[8:11]
	v_mfma_f32_16x16x32_bf16 v[16:19], v[132:135], v[236:239], v[16:19]
	s_setprio 0
	s_setprio 1
	v_mfma_f32_16x16x32_bf16 v[52:55], v[144:147], v[190:193], v[52:55]
	v_mfma_f32_16x16x32_bf16 v[44:47], v[182:185], v[190:193], v[44:47]
	v_mfma_f32_16x16x32_bf16 v[28:31], v[182:185], v[214:217], v[28:31]
	v_mfma_f32_16x16x32_bf16 v[36:39], v[144:147], v[214:217], v[36:39]
	v_mfma_f32_16x16x32_bf16 v[20:23], v[144:147], v[224:227], v[20:23]
	v_mfma_f32_16x16x32_bf16 v[12:15], v[182:185], v[224:227], v[12:15]
	v_mfma_f32_16x16x32_bf16 v[0:3], v[182:185], v[232:235], v[0:3]
	v_mfma_f32_16x16x32_bf16 v[4:7], v[144:147], v[232:235], v[4:7]
	v_mfma_f32_16x16x32_bf16 v[52:55], v[148:151], v[210:213], v[52:55]
	v_mfma_f32_16x16x32_bf16 v[44:47], v[186:189], v[210:213], v[44:47]
	v_mfma_f32_16x16x32_bf16 v[28:31], v[186:189], v[218:221], v[28:31]
	v_mfma_f32_16x16x32_bf16 v[36:39], v[148:151], v[218:221], v[36:39]
	v_mfma_f32_16x16x32_bf16 v[20:23], v[148:151], v[228:231], v[20:23]
	v_mfma_f32_16x16x32_bf16 v[12:15], v[186:189], v[228:231], v[12:15]
	v_mfma_f32_16x16x32_bf16 v[0:3], v[186:189], v[236:239], v[0:3]
	v_mfma_f32_16x16x32_bf16 v[4:7], v[148:151], v[236:239], v[4:7]
	s_setprio 0
	s_barrier
	s_add_i32 s82, s82, 2
	s_add_u32 s80, s80, 0x100
	s_addc_u32 s81, s81, 0
	s_add_u32 s60, s60, 0x100
	s_addc_u32 s61, s61, 0
	s_cmp_gt_u32 s82, 5
	.p2align	6

.LBB0_724:
	s_ashr_i32 s21, s20, 31
	s_lshl_b64 s[48:49], s[20:21], 18
	v_readlane_b32 s19, v254, 28
	s_add_u32 s48, s19, s48
	v_readlane_b32 s19, v254, 29
	s_addc_u32 s49, s19, s49
	s_and_b64 s[50:51], s[46:47], exec
	s_cselect_b32 s21, s49, s45
	s_cselect_b32 s78, s48, s44
	s_ashr_i32 s19, s18, 31
	s_lshl_b64 s[50:51], s[18:19], 18
	v_readlane_b32 s19, v254, 24
	s_add_u32 s50, s19, s50
	v_readlane_b32 s19, v254, 25
	s_addc_u32 s51, s19, s51
	s_and_b64 s[62:63], s[46:47], exec
	s_cselect_b32 s19, s51, s61
	s_cselect_b32 s79, s50, s60
	s_add_u32 s80, s60, 0x100
	s_addc_u32 s81, s61, 0
	s_add_u32 s60, s44, 0x20080
	s_addc_u32 s61, s45, 0
	s_mov_b32 s82, -2
	s_add_u32 s44, s60, 0xfffe0080
	s_addc_u32 s45, s61, -1
	s_cmp_eq_u32 s82, 4
	s_cselect_b32 s63, s21, s45
	s_cselect_b32 s62, s78, s44
	s_cselect_b32 s45, s19, s81
	s_cselect_b32 s44, s79, s80
	v_lshl_add_u64 v[178:179], s[60:61], 0, v[172:173]
	s_add_i32 m0, s59, 0xc000
	global_load_lds_dwordx4 v[178:179], off
	v_lshl_add_u64 v[178:179], s[60:61], 0, v[150:151]
	s_add_i32 m0, s59, 0xe000
	s_nop 0
	global_load_lds_dwordx4 v[178:179], off
	s_waitcnt vmcnt(8)
	s_waitcnt lgkmcnt(0)
	s_barrier
	s_setprio 1
	s_waitcnt lgkmcnt(0)
	v_mfma_f32_16x16x32_bf16 v[124:127], v[128:131], v[196:199], 0
	v_mfma_f32_16x16x32_bf16 v[120:123], v[136:139], v[196:199], 0
	v_mfma_f32_16x16x32_bf16 v[108:111], v[128:131], v[214:217], 0
	v_mfma_f32_16x16x32_bf16 v[104:107], v[136:139], v[214:217], 0
	v_mfma_f32_16x16x32_bf16 v[92:95], v[128:131], v[224:227], 0
	v_mfma_f32_16x16x32_bf16 v[88:91], v[136:139], v[224:227], 0
	v_mfma_f32_16x16x32_bf16 v[76:79], v[128:131], v[232:235], 0
	v_mfma_f32_16x16x32_bf16 v[72:75], v[136:139], v[232:235], 0
	v_mfma_f32_16x16x32_bf16 v[124:127], v[132:135], v[210:213], v[124:127]
	v_mfma_f32_16x16x32_bf16 v[120:123], v[140:143], v[210:213], v[120:123]
	v_mfma_f32_16x16x32_bf16 v[104:107], v[140:143], v[218:221], v[104:107]
	v_mfma_f32_16x16x32_bf16 v[108:111], v[132:135], v[218:221], v[108:111]
	v_mfma_f32_16x16x32_bf16 v[92:95], v[132:135], v[228:231], v[92:95]
	v_mfma_f32_16x16x32_bf16 v[88:91], v[140:143], v[228:231], v[88:91]
	v_mfma_f32_16x16x32_bf16 v[72:75], v[140:143], v[236:239], v[72:75]
	v_mfma_f32_16x16x32_bf16 v[76:79], v[132:135], v[236:239], v[76:79]
	s_setprio 0
	s_setprio 1
	v_mfma_f32_16x16x32_bf16 v[116:119], v[174:177], v[196:199], 0
	v_mfma_f32_16x16x32_bf16 v[112:115], v[188:191], v[196:199], 0
	v_mfma_f32_16x16x32_bf16 v[100:103], v[174:177], v[214:217], 0
	v_mfma_f32_16x16x32_bf16 v[96:99], v[188:191], v[214:217], 0
	v_mfma_f32_16x16x32_bf16 v[84:87], v[174:177], v[224:227], 0
	v_mfma_f32_16x16x32_bf16 v[80:83], v[188:191], v[224:227], 0
	v_mfma_f32_16x16x32_bf16 v[68:71], v[174:177], v[232:235], 0
	v_mfma_f32_16x16x32_bf16 v[64:67], v[188:191], v[232:235], 0
	v_mfma_f32_16x16x32_bf16 v[116:119], v[184:187], v[210:213], v[116:119]
	v_mfma_f32_16x16x32_bf16 v[112:115], v[192:195], v[210:213], v[112:115]
	v_mfma_f32_16x16x32_bf16 v[96:99], v[192:195], v[218:221], v[96:99]
	v_mfma_f32_16x16x32_bf16 v[100:103], v[184:187], v[218:221], v[100:103]
	v_mfma_f32_16x16x32_bf16 v[84:87], v[184:187], v[228:231], v[84:87]
	v_mfma_f32_16x16x32_bf16 v[80:83], v[192:195], v[228:231], v[80:83]
	v_mfma_f32_16x16x32_bf16 v[64:67], v[192:195], v[236:239], v[64:67]
	v_mfma_f32_16x16x32_bf16 v[68:71], v[184:187], v[236:239], v[68:71]
	s_setprio 0
	s_barrier
	s_add_i32 s83, s83, s8
	v_lshl_add_u64 v[178:179], s[44:45], 0, v[152:153]
	s_mov_b32 m0, s83
	ds_read_b128 v[196:199], v183 offset:16384
	ds_read_b128 v[210:213], v183 offset:17408
	ds_read_b128 v[214:217], v183 offset:18432
	ds_read_b128 v[218:221], v183 offset:19456
	ds_read_b128 v[224:227], v183 offset:20480
	ds_read_b128 v[228:231], v183 offset:21504
	ds_read_b128 v[232:235], v183 offset:22528
	ds_read_b128 v[236:239], v183 offset:23552
	global_load_lds_dwordx4 v[178:179], off
	s_add_i32 m0, s83, 0x2000
	s_add_u32 s84, s44, 0x20000
	v_lshl_add_u64 v[240:241], s[44:45], 0, v[144:145]
	s_addc_u32 s85, s45, 0
	s_add_i32 s83, s86, s8
	global_load_lds_dwordx4 v[240:241], off
	v_lshl_add_u64 v[242:243], s[84:85], 0, v[152:153]
	s_mov_b32 m0, s83
	v_lshl_add_u64 v[244:245], s[62:63], 0, v[146:147]
	global_load_lds_dwordx4 v[242:243], off
	v_lshl_add_u64 v[242:243], s[84:85], 0, v[144:145]
	s_add_i32 m0, s83, 0x2000
	s_nop 0
	global_load_lds_dwordx4 v[242:243], off
	v_lshl_add_u64 v[242:243], s[62:63], 0, v[148:149]
	s_mov_b32 m0, s59
	s_nop 0
	global_load_lds_dwordx4 v[242:243], off
	s_mov_b32 m0, s66
	s_nop 0
	global_load_lds_dwordx4 v[244:245], off
	s_waitcnt vmcnt(8)
	s_waitcnt lgkmcnt(0)
	s_barrier
	s_setprio 1
	s_waitcnt lgkmcnt(0)
	v_mfma_f32_16x16x32_bf16 v[60:63], v[128:131], v[196:199], 0
	v_mfma_f32_16x16x32_bf16 v[56:59], v[136:139], v[196:199], 0
	v_mfma_f32_16x16x32_bf16 v[44:47], v[128:131], v[214:217], 0
	v_mfma_f32_16x16x32_bf16 v[40:43], v[136:139], v[214:217], 0
	v_mfma_f32_16x16x32_bf16 v[28:31], v[128:131], v[224:227], 0
	v_mfma_f32_16x16x32_bf16 v[24:27], v[136:139], v[224:227], 0
	v_mfma_f32_16x16x32_bf16 v[12:15], v[128:131], v[232:235], 0
	v_mfma_f32_16x16x32_bf16 v[8:11], v[136:139], v[232:235], 0
	v_mfma_f32_16x16x32_bf16 v[60:63], v[132:135], v[210:213], v[60:63]
	v_mfma_f32_16x16x32_bf16 v[56:59], v[140:143], v[210:213], v[56:59]
	v_mfma_f32_16x16x32_bf16 v[40:43], v[140:143], v[218:221], v[40:43]
	v_mfma_f32_16x16x32_bf16 v[44:47], v[132:135], v[218:221], v[44:47]
	v_mfma_f32_16x16x32_bf16 v[28:31], v[132:135], v[228:231], v[28:31]
	v_mfma_f32_16x16x32_bf16 v[24:27], v[140:143], v[228:231], v[24:27]
	v_mfma_f32_16x16x32_bf16 v[8:11], v[140:143], v[236:239], v[8:11]
	v_mfma_f32_16x16x32_bf16 v[12:15], v[132:135], v[236:239], v[12:15]
	s_setprio 0
	s_setprio 1
	v_mfma_f32_16x16x32_bf16 v[52:55], v[174:177], v[196:199], 0
	v_mfma_f32_16x16x32_bf16 v[48:51], v[188:191], v[196:199], 0
	v_mfma_f32_16x16x32_bf16 v[36:39], v[174:177], v[214:217], 0
	v_mfma_f32_16x16x32_bf16 v[32:35], v[188:191], v[214:217], 0
	v_mfma_f32_16x16x32_bf16 v[20:23], v[174:177], v[224:227], 0
	v_mfma_f32_16x16x32_bf16 v[16:19], v[188:191], v[224:227], 0
	v_mfma_f32_16x16x32_bf16 v[4:7], v[174:177], v[232:235], 0
	v_mfma_f32_16x16x32_bf16 v[0:3], v[188:191], v[232:235], 0
	v_mfma_f32_16x16x32_bf16 v[52:55], v[184:187], v[210:213], v[52:55]
	v_mfma_f32_16x16x32_bf16 v[48:51], v[192:195], v[210:213], v[48:51]
	v_mfma_f32_16x16x32_bf16 v[32:35], v[192:195], v[218:221], v[32:35]
	v_mfma_f32_16x16x32_bf16 v[36:39], v[184:187], v[218:221], v[36:39]
	v_mfma_f32_16x16x32_bf16 v[20:23], v[184:187], v[228:231], v[20:23]
	v_mfma_f32_16x16x32_bf16 v[16:19], v[192:195], v[228:231], v[16:19]
	v_mfma_f32_16x16x32_bf16 v[0:3], v[192:195], v[236:239], v[0:3]
	v_mfma_f32_16x16x32_bf16 v[4:7], v[184:187], v[236:239], v[4:7]
	s_setprio 0
	s_barrier
	s_add_i32 s83, 0, 0x18000
	s_add_i32 s84, 0, 0x1c000
	v_add_u32_e32 v140, s83, v181
	v_add_u32_e32 v192, s84, v181
	ds_read_b128 v[128:131], v140
	ds_read_b128 v[132:135], v140 offset:1024
	ds_read_b128 v[136:139], v140 offset:2048
	ds_read_b128 v[140:143], v140 offset:3072
	ds_read_b128 v[174:177], v192
	ds_read_b128 v[184:187], v192 offset:1024
	ds_read_b128 v[188:191], v192 offset:2048
	ds_read_b128 v[192:195], v192 offset:3072
	s_add_u32 s62, s62, 0x20000
	s_addc_u32 s63, s63, 0
	s_mov_b32 m0, s67
	v_lshl_add_u64 v[246:247], s[62:63], 0, v[148:149]
	ds_read_b128 v[196:199], v183 offset:32768
	ds_read_b128 v[210:213], v183 offset:33792
	ds_read_b128 v[214:217], v183 offset:34816
	ds_read_b128 v[218:221], v183 offset:35840
	ds_read_b128 v[224:227], v183 offset:36864
	ds_read_b128 v[228:231], v183 offset:37888
	ds_read_b128 v[232:235], v183 offset:38912
	ds_read_b128 v[236:239], v183 offset:39936
	global_load_lds_dwordx4 v[246:247], off
	v_lshl_add_u64 v[246:247], s[62:63], 0, v[146:147]
	s_mov_b32 m0, s68
	s_nop 0
	global_load_lds_dwordx4 v[246:247], off
	s_waitcnt vmcnt(8)
	s_waitcnt lgkmcnt(0)
	s_barrier
	s_setprio 1
	s_waitcnt lgkmcnt(0)
	v_mfma_f32_16x16x32_bf16 v[124:127], v[128:131], v[196:199], v[124:127]
	v_mfma_f32_16x16x32_bf16 v[120:123], v[136:139], v[196:199], v[120:123]
	v_mfma_f32_16x16x32_bf16 v[104:107], v[136:139], v[214:217], v[104:107]
	v_mfma_f32_16x16x32_bf16 v[108:111], v[128:131], v[214:217], v[108:111]
	v_mfma_f32_16x16x32_bf16 v[92:95], v[128:131], v[224:227], v[92:95]
	v_mfma_f32_16x16x32_bf16 v[88:91], v[136:139], v[224:227], v[88:91]
	v_mfma_f32_16x16x32_bf16 v[72:75], v[136:139], v[232:235], v[72:75]
	v_mfma_f32_16x16x32_bf16 v[76:79], v[128:131], v[232:235], v[76:79]
	v_mfma_f32_16x16x32_bf16 v[124:127], v[132:135], v[210:213], v[124:127]
	v_mfma_f32_16x16x32_bf16 v[120:123], v[140:143], v[210:213], v[120:123]
	v_mfma_f32_16x16x32_bf16 v[104:107], v[140:143], v[218:221], v[104:107]
	v_mfma_f32_16x16x32_bf16 v[108:111], v[132:135], v[218:221], v[108:111]
	v_mfma_f32_16x16x32_bf16 v[92:95], v[132:135], v[228:231], v[92:95]
	v_mfma_f32_16x16x32_bf16 v[88:91], v[140:143], v[228:231], v[88:91]
	v_mfma_f32_16x16x32_bf16 v[72:75], v[140:143], v[236:239], v[72:75]
	v_mfma_f32_16x16x32_bf16 v[76:79], v[132:135], v[236:239], v[76:79]
	s_setprio 0
	s_setprio 1
	v_mfma_f32_16x16x32_bf16 v[116:119], v[174:177], v[196:199], v[116:119]
	v_mfma_f32_16x16x32_bf16 v[112:115], v[188:191], v[196:199], v[112:115]
	v_mfma_f32_16x16x32_bf16 v[96:99], v[188:191], v[214:217], v[96:99]
	v_mfma_f32_16x16x32_bf16 v[100:103], v[174:177], v[214:217], v[100:103]
	v_mfma_f32_16x16x32_bf16 v[84:87], v[174:177], v[224:227], v[84:87]
	v_mfma_f32_16x16x32_bf16 v[80:83], v[188:191], v[224:227], v[80:83]
	v_mfma_f32_16x16x32_bf16 v[64:67], v[188:191], v[232:235], v[64:67]
	v_mfma_f32_16x16x32_bf16 v[68:71], v[174:177], v[232:235], v[68:71]
	v_mfma_f32_16x16x32_bf16 v[116:119], v[184:187], v[210:213], v[116:119]
	v_mfma_f32_16x16x32_bf16 v[112:115], v[192:195], v[210:213], v[112:115]
	v_mfma_f32_16x16x32_bf16 v[96:99], v[192:195], v[218:221], v[96:99]
	v_mfma_f32_16x16x32_bf16 v[100:103], v[184:187], v[218:221], v[100:103]
	v_mfma_f32_16x16x32_bf16 v[84:87], v[184:187], v[228:231], v[84:87]
	v_mfma_f32_16x16x32_bf16 v[80:83], v[192:195], v[228:231], v[80:83]
	v_mfma_f32_16x16x32_bf16 v[64:67], v[192:195], v[236:239], v[64:67]
	v_mfma_f32_16x16x32_bf16 v[68:71], v[184:187], v[236:239], v[68:71]
	s_setprio 0
	s_barrier
	s_add_i32 s62, s83, s8
	v_lshl_add_u64 v[178:179], v[178:179], 0, s[22:23]
	s_mov_b32 m0, s62
	ds_read_b128 v[196:199], v183 offset:49152
	ds_read_b128 v[210:213], v183 offset:50176
	ds_read_b128 v[214:217], v183 offset:51200
	ds_read_b128 v[218:221], v183 offset:52224
	ds_read_b128 v[224:227], v183 offset:53248
	ds_read_b128 v[228:231], v183 offset:54272
	ds_read_b128 v[232:235], v183 offset:55296
	ds_read_b128 v[236:239], v183 offset:56320
	global_load_lds_dwordx4 v[178:179], off
	s_add_i32 m0, s62, 0x2000
	s_add_u32 s44, s44, 0x20080
	v_lshl_add_u64 v[178:179], v[240:241], 0, s[22:23]
	s_addc_u32 s45, s45, 0
	s_add_i32 s62, s84, s8
	global_load_lds_dwordx4 v[178:179], off
	v_lshl_add_u64 v[178:179], s[44:45], 0, v[152:153]
	s_mov_b32 m0, s62
	s_nop 0
	global_load_lds_dwordx4 v[178:179], off
	v_lshl_add_u64 v[178:179], s[44:45], 0, v[144:145]
	s_add_i32 m0, s62, 0x2000
	s_nop 0
	global_load_lds_dwordx4 v[178:179], off
	v_lshl_add_u64 v[178:179], v[242:243], 0, s[22:23]
	s_mov_b32 m0, s69
	s_nop 0
	global_load_lds_dwordx4 v[178:179], off
	v_lshl_add_u64 v[178:179], v[244:245], 0, s[22:23]
	s_mov_b32 m0, s74
	s_nop 0
	global_load_lds_dwordx4 v[178:179], off
	s_waitcnt vmcnt(8)
	s_waitcnt lgkmcnt(0)
	s_barrier
	s_setprio 1
	s_waitcnt lgkmcnt(0)
	v_mfma_f32_16x16x32_bf16 v[60:63], v[128:131], v[196:199], v[60:63]
	v_mfma_f32_16x16x32_bf16 v[56:59], v[136:139], v[196:199], v[56:59]
	v_mfma_f32_16x16x32_bf16 v[40:43], v[136:139], v[214:217], v[40:43]
	v_mfma_f32_16x16x32_bf16 v[44:47], v[128:131], v[214:217], v[44:47]
	v_mfma_f32_16x16x32_bf16 v[28:31], v[128:131], v[224:227], v[28:31]
	v_mfma_f32_16x16x32_bf16 v[24:27], v[136:139], v[224:227], v[24:27]
	v_mfma_f32_16x16x32_bf16 v[8:11], v[136:139], v[232:235], v[8:11]
	v_mfma_f32_16x16x32_bf16 v[12:15], v[128:131], v[232:235], v[12:15]
	v_mfma_f32_16x16x32_bf16 v[60:63], v[132:135], v[210:213], v[60:63]
	v_mfma_f32_16x16x32_bf16 v[56:59], v[140:143], v[210:213], v[56:59]
	v_mfma_f32_16x16x32_bf16 v[40:43], v[140:143], v[218:221], v[40:43]
	v_mfma_f32_16x16x32_bf16 v[44:47], v[132:135], v[218:221], v[44:47]
	v_mfma_f32_16x16x32_bf16 v[28:31], v[132:135], v[228:231], v[28:31]
	v_mfma_f32_16x16x32_bf16 v[24:27], v[140:143], v[228:231], v[24:27]
	v_mfma_f32_16x16x32_bf16 v[8:11], v[140:143], v[236:239], v[8:11]
	v_mfma_f32_16x16x32_bf16 v[12:15], v[132:135], v[236:239], v[12:15]
	s_setprio 0
	s_setprio 1
	v_mfma_f32_16x16x32_bf16 v[52:55], v[174:177], v[196:199], v[52:55]
	v_mfma_f32_16x16x32_bf16 v[48:51], v[188:191], v[196:199], v[48:51]
	v_mfma_f32_16x16x32_bf16 v[32:35], v[188:191], v[214:217], v[32:35]
	v_mfma_f32_16x16x32_bf16 v[36:39], v[174:177], v[214:217], v[36:39]
	v_mfma_f32_16x16x32_bf16 v[20:23], v[174:177], v[224:227], v[20:23]
	v_mfma_f32_16x16x32_bf16 v[16:19], v[188:191], v[224:227], v[16:19]
	v_mfma_f32_16x16x32_bf16 v[0:3], v[188:191], v[232:235], v[0:3]
	v_mfma_f32_16x16x32_bf16 v[4:7], v[174:177], v[232:235], v[4:7]
	v_mfma_f32_16x16x32_bf16 v[52:55], v[184:187], v[210:213], v[52:55]
	v_mfma_f32_16x16x32_bf16 v[48:51], v[192:195], v[210:213], v[48:51]
	v_mfma_f32_16x16x32_bf16 v[32:35], v[192:195], v[218:221], v[32:35]
	v_mfma_f32_16x16x32_bf16 v[36:39], v[184:187], v[218:221], v[36:39]
	v_mfma_f32_16x16x32_bf16 v[20:23], v[184:187], v[228:231], v[20:23]
	v_mfma_f32_16x16x32_bf16 v[16:19], v[192:195], v[228:231], v[16:19]
	v_mfma_f32_16x16x32_bf16 v[0:3], v[192:195], v[236:239], v[0:3]
	v_mfma_f32_16x16x32_bf16 v[4:7], v[184:187], v[236:239], v[4:7]
	s_setprio 0
	s_barrier
	s_add_i32 s82, s82, 2
	s_add_u32 s80, s80, 0x100
	s_addc_u32 s81, s81, 0
	s_add_u32 s60, s60, 0x100
	s_addc_u32 s61, s61, 0
	s_cmp_gt_u32 s82, 5
	.p2align	6

.LBB0_821:
	s_ashr_i32 s21, s20, 31
	s_lshl_b64 s[48:49], s[20:21], 19
	s_add_u32 s48, s70, s48
	s_addc_u32 s49, s71, s49
	s_and_b64 s[50:51], s[46:47], exec
	s_cselect_b32 s21, s49, s61
	s_cselect_b32 s81, s48, s60
	s_ashr_i32 s19, s18, 31
	s_lshl_b64 s[50:51], s[18:19], 19
	v_readlane_b32 s19, v254, 54
	s_add_u32 s50, s19, s50
	v_readlane_b32 s19, v254, 55
	s_addc_u32 s51, s19, s51
	s_and_b64 s[66:67], s[46:47], exec
	s_cselect_b32 s19, s51, s63
	s_cselect_b32 s82, s50, s62
	s_add_u32 s83, s62, 0x100
	s_addc_u32 s84, s63, 0
	s_add_u32 s60, s60, 0x40080
	s_addc_u32 s61, s61, 0
	s_mov_b32 s85, -2
	s_add_u32 s62, s60, 0xfffc0080
	s_addc_u32 s63, s61, -1
	s_cmp_eq_u32 s85, 12
	s_cselect_b32 s67, s21, s63
	s_cselect_b32 s66, s81, s62
	s_cselect_b32 s63, s19, s84
	s_cselect_b32 s62, s82, s83
	v_lshl_add_u64 v[198:199], s[60:61], 0, v[180:181]
	s_add_i32 m0, s68, 0xc000
	global_load_lds_dwordx4 v[198:199], off
	v_lshl_add_u64 v[198:199], s[60:61], 0, v[178:179]
	s_add_i32 m0, s68, 0xe000
	s_nop 0
	global_load_lds_dwordx4 v[198:199], off
	s_waitcnt vmcnt(8)
	s_waitcnt lgkmcnt(0)
	s_barrier
	s_setprio 1
	s_waitcnt lgkmcnt(0)
	v_mfma_f32_16x16x32_bf16 v[148:151], v[112:115], v[190:193], 0
	v_mfma_f32_16x16x32_bf16 v[144:147], v[120:123], v[190:193], 0
	v_mfma_f32_16x16x32_bf16 v[108:111], v[112:115], v[214:217], 0
	v_mfma_f32_16x16x32_bf16 v[104:107], v[120:123], v[214:217], 0
	v_mfma_f32_16x16x32_bf16 v[92:95], v[112:115], v[224:227], 0
	v_mfma_f32_16x16x32_bf16 v[88:91], v[120:123], v[224:227], 0
	v_mfma_f32_16x16x32_bf16 v[76:79], v[112:115], v[232:235], 0
	v_mfma_f32_16x16x32_bf16 v[72:75], v[120:123], v[232:235], 0
	v_mfma_f32_16x16x32_bf16 v[148:151], v[116:119], v[194:197], v[148:151]
	v_mfma_f32_16x16x32_bf16 v[144:147], v[124:127], v[194:197], v[144:147]
	v_mfma_f32_16x16x32_bf16 v[104:107], v[124:127], v[218:221], v[104:107]
	v_mfma_f32_16x16x32_bf16 v[108:111], v[116:119], v[218:221], v[108:111]
	v_mfma_f32_16x16x32_bf16 v[92:95], v[116:119], v[228:231], v[92:95]
	v_mfma_f32_16x16x32_bf16 v[88:91], v[124:127], v[228:231], v[88:91]
	v_mfma_f32_16x16x32_bf16 v[72:75], v[124:127], v[236:239], v[72:75]
	v_mfma_f32_16x16x32_bf16 v[76:79], v[116:119], v[236:239], v[76:79]
	s_setprio 0
	s_setprio 1
	v_mfma_f32_16x16x32_bf16 v[136:139], v[132:135], v[190:193], 0
	v_mfma_f32_16x16x32_bf16 v[128:131], v[182:185], v[190:193], 0
	v_mfma_f32_16x16x32_bf16 v[100:103], v[132:135], v[214:217], 0
	v_mfma_f32_16x16x32_bf16 v[96:99], v[182:185], v[214:217], 0
	v_mfma_f32_16x16x32_bf16 v[84:87], v[132:135], v[224:227], 0
	v_mfma_f32_16x16x32_bf16 v[80:83], v[182:185], v[224:227], 0
	v_mfma_f32_16x16x32_bf16 v[68:71], v[132:135], v[232:235], 0
	v_mfma_f32_16x16x32_bf16 v[64:67], v[182:185], v[232:235], 0
	v_mfma_f32_16x16x32_bf16 v[136:139], v[140:143], v[194:197], v[136:139]
	v_mfma_f32_16x16x32_bf16 v[128:131], v[186:189], v[194:197], v[128:131]
	v_mfma_f32_16x16x32_bf16 v[96:99], v[186:189], v[218:221], v[96:99]
	v_mfma_f32_16x16x32_bf16 v[100:103], v[140:143], v[218:221], v[100:103]
	v_mfma_f32_16x16x32_bf16 v[84:87], v[140:143], v[228:231], v[84:87]
	v_mfma_f32_16x16x32_bf16 v[80:83], v[186:189], v[228:231], v[80:83]
	v_mfma_f32_16x16x32_bf16 v[64:67], v[186:189], v[236:239], v[64:67]
	v_mfma_f32_16x16x32_bf16 v[68:71], v[140:143], v[236:239], v[68:71]
	s_setprio 0
	s_barrier
	s_add_i32 s86, s86, s59
	v_lshl_add_u64 v[198:199], s[62:63], 0, v[152:153]
	s_mov_b32 m0, s86
	ds_read_b128 v[190:193], v212 offset:16384
	ds_read_b128 v[194:197], v212 offset:17408
	ds_read_b128 v[214:217], v212 offset:18432
	ds_read_b128 v[218:221], v212 offset:19456
	ds_read_b128 v[224:227], v212 offset:20480
	ds_read_b128 v[228:231], v212 offset:21504
	ds_read_b128 v[232:235], v212 offset:22528
	ds_read_b128 v[236:239], v212 offset:23552
	global_load_lds_dwordx4 v[198:199], off
	s_add_i32 m0, s86, 0x2000
	s_add_u32 s86, s62, 0x40000
	v_lshl_add_u64 v[240:241], s[62:63], 0, v[172:173]
	s_addc_u32 s87, s63, 0
	s_add_i32 s89, s89, s59
	global_load_lds_dwordx4 v[240:241], off
	v_lshl_add_u64 v[242:243], s[86:87], 0, v[152:153]
	s_mov_b32 m0, s89
	v_lshl_add_u64 v[244:245], s[66:67], 0, v[174:175]
	global_load_lds_dwordx4 v[242:243], off
	v_lshl_add_u64 v[242:243], s[86:87], 0, v[172:173]
	s_add_i32 m0, s89, 0x2000
	s_nop 0
	global_load_lds_dwordx4 v[242:243], off
	v_lshl_add_u64 v[242:243], s[66:67], 0, v[176:177]
	s_mov_b32 m0, s68
	s_nop 0
	global_load_lds_dwordx4 v[242:243], off
	s_mov_b32 m0, s69
	s_nop 0
	global_load_lds_dwordx4 v[244:245], off
	s_waitcnt vmcnt(8)
	s_waitcnt lgkmcnt(0)
	s_barrier
	s_setprio 1
	s_waitcnt lgkmcnt(0)
	v_mfma_f32_16x16x32_bf16 v[60:63], v[112:115], v[190:193], 0
	v_mfma_f32_16x16x32_bf16 v[56:59], v[120:123], v[190:193], 0
	v_mfma_f32_16x16x32_bf16 v[44:47], v[112:115], v[214:217], 0
	v_mfma_f32_16x16x32_bf16 v[40:43], v[120:123], v[214:217], 0
	v_mfma_f32_16x16x32_bf16 v[28:31], v[112:115], v[224:227], 0
	v_mfma_f32_16x16x32_bf16 v[24:27], v[120:123], v[224:227], 0
	v_mfma_f32_16x16x32_bf16 v[12:15], v[112:115], v[232:235], 0
	v_mfma_f32_16x16x32_bf16 v[8:11], v[120:123], v[232:235], 0
	v_mfma_f32_16x16x32_bf16 v[60:63], v[116:119], v[194:197], v[60:63]
	v_mfma_f32_16x16x32_bf16 v[56:59], v[124:127], v[194:197], v[56:59]
	v_mfma_f32_16x16x32_bf16 v[40:43], v[124:127], v[218:221], v[40:43]
	v_mfma_f32_16x16x32_bf16 v[44:47], v[116:119], v[218:221], v[44:47]
	v_mfma_f32_16x16x32_bf16 v[28:31], v[116:119], v[228:231], v[28:31]
	v_mfma_f32_16x16x32_bf16 v[24:27], v[124:127], v[228:231], v[24:27]
	v_mfma_f32_16x16x32_bf16 v[8:11], v[124:127], v[236:239], v[8:11]
	v_mfma_f32_16x16x32_bf16 v[12:15], v[116:119], v[236:239], v[12:15]
	s_setprio 0
	s_setprio 1
	v_mfma_f32_16x16x32_bf16 v[52:55], v[132:135], v[190:193], 0
	v_mfma_f32_16x16x32_bf16 v[48:51], v[182:185], v[190:193], 0
	v_mfma_f32_16x16x32_bf16 v[36:39], v[132:135], v[214:217], 0
	v_mfma_f32_16x16x32_bf16 v[32:35], v[182:185], v[214:217], 0
	v_mfma_f32_16x16x32_bf16 v[20:23], v[132:135], v[224:227], 0
	v_mfma_f32_16x16x32_bf16 v[16:19], v[182:185], v[224:227], 0
	v_mfma_f32_16x16x32_bf16 v[4:7], v[132:135], v[232:235], 0
	v_mfma_f32_16x16x32_bf16 v[0:3], v[182:185], v[232:235], 0
	v_mfma_f32_16x16x32_bf16 v[52:55], v[140:143], v[194:197], v[52:55]
	v_mfma_f32_16x16x32_bf16 v[48:51], v[186:189], v[194:197], v[48:51]
	v_mfma_f32_16x16x32_bf16 v[32:35], v[186:189], v[218:221], v[32:35]
	v_mfma_f32_16x16x32_bf16 v[36:39], v[140:143], v[218:221], v[36:39]
	v_mfma_f32_16x16x32_bf16 v[20:23], v[140:143], v[228:231], v[20:23]
	v_mfma_f32_16x16x32_bf16 v[16:19], v[186:189], v[228:231], v[16:19]
	v_mfma_f32_16x16x32_bf16 v[0:3], v[186:189], v[236:239], v[0:3]
	v_mfma_f32_16x16x32_bf16 v[4:7], v[140:143], v[236:239], v[4:7]
	s_setprio 0
	s_barrier
	s_add_i32 s86, 0, 0x18000
	s_add_i32 s87, 0, 0x1c000
	v_add_u32_e32 v124, s86, v210
	v_add_u32_e32 v186, s87, v210
	ds_read_b128 v[112:115], v124
	ds_read_b128 v[116:119], v124 offset:1024
	ds_read_b128 v[120:123], v124 offset:2048
	ds_read_b128 v[124:127], v124 offset:3072
	ds_read_b128 v[132:135], v186
	ds_read_b128 v[140:143], v186 offset:1024
	ds_read_b128 v[182:185], v186 offset:2048
	ds_read_b128 v[186:189], v186 offset:3072
	s_add_u32 s66, s66, 0x40000
	s_addc_u32 s67, s67, 0
	s_mov_b32 m0, s74
	v_lshl_add_u64 v[246:247], s[66:67], 0, v[176:177]
	ds_read_b128 v[190:193], v212 offset:32768
	ds_read_b128 v[194:197], v212 offset:33792
	ds_read_b128 v[214:217], v212 offset:34816
	ds_read_b128 v[218:221], v212 offset:35840
	ds_read_b128 v[224:227], v212 offset:36864
	ds_read_b128 v[228:231], v212 offset:37888
	ds_read_b128 v[232:235], v212 offset:38912
	ds_read_b128 v[236:239], v212 offset:39936
	global_load_lds_dwordx4 v[246:247], off
	v_lshl_add_u64 v[246:247], s[66:67], 0, v[174:175]
	s_mov_b32 m0, s75
	s_nop 0
	global_load_lds_dwordx4 v[246:247], off
	s_waitcnt vmcnt(8)
	s_waitcnt lgkmcnt(0)
	s_barrier
	s_setprio 1
	s_waitcnt lgkmcnt(0)
	v_mfma_f32_16x16x32_bf16 v[148:151], v[112:115], v[190:193], v[148:151]
	v_mfma_f32_16x16x32_bf16 v[144:147], v[120:123], v[190:193], v[144:147]
	v_mfma_f32_16x16x32_bf16 v[104:107], v[120:123], v[214:217], v[104:107]
	v_mfma_f32_16x16x32_bf16 v[108:111], v[112:115], v[214:217], v[108:111]
	v_mfma_f32_16x16x32_bf16 v[92:95], v[112:115], v[224:227], v[92:95]
	v_mfma_f32_16x16x32_bf16 v[88:91], v[120:123], v[224:227], v[88:91]
	v_mfma_f32_16x16x32_bf16 v[72:75], v[120:123], v[232:235], v[72:75]
	v_mfma_f32_16x16x32_bf16 v[76:79], v[112:115], v[232:235], v[76:79]
	v_mfma_f32_16x16x32_bf16 v[148:151], v[116:119], v[194:197], v[148:151]
	v_mfma_f32_16x16x32_bf16 v[144:147], v[124:127], v[194:197], v[144:147]
	v_mfma_f32_16x16x32_bf16 v[104:107], v[124:127], v[218:221], v[104:107]
	v_mfma_f32_16x16x32_bf16 v[108:111], v[116:119], v[218:221], v[108:111]
	v_mfma_f32_16x16x32_bf16 v[92:95], v[116:119], v[228:231], v[92:95]
	v_mfma_f32_16x16x32_bf16 v[88:91], v[124:127], v[228:231], v[88:91]
	v_mfma_f32_16x16x32_bf16 v[72:75], v[124:127], v[236:239], v[72:75]
	v_mfma_f32_16x16x32_bf16 v[76:79], v[116:119], v[236:239], v[76:79]
	s_setprio 0
	s_setprio 1
	v_mfma_f32_16x16x32_bf16 v[136:139], v[132:135], v[190:193], v[136:139]
	v_mfma_f32_16x16x32_bf16 v[128:131], v[182:185], v[190:193], v[128:131]
	v_mfma_f32_16x16x32_bf16 v[96:99], v[182:185], v[214:217], v[96:99]
	v_mfma_f32_16x16x32_bf16 v[100:103], v[132:135], v[214:217], v[100:103]
	v_mfma_f32_16x16x32_bf16 v[84:87], v[132:135], v[224:227], v[84:87]
	v_mfma_f32_16x16x32_bf16 v[80:83], v[182:185], v[224:227], v[80:83]
	v_mfma_f32_16x16x32_bf16 v[64:67], v[182:185], v[232:235], v[64:67]
	v_mfma_f32_16x16x32_bf16 v[68:71], v[132:135], v[232:235], v[68:71]
	v_mfma_f32_16x16x32_bf16 v[136:139], v[140:143], v[194:197], v[136:139]
	v_mfma_f32_16x16x32_bf16 v[128:131], v[186:189], v[194:197], v[128:131]
	v_mfma_f32_16x16x32_bf16 v[96:99], v[186:189], v[218:221], v[96:99]
	v_mfma_f32_16x16x32_bf16 v[100:103], v[140:143], v[218:221], v[100:103]
	v_mfma_f32_16x16x32_bf16 v[84:87], v[140:143], v[228:231], v[84:87]
	v_mfma_f32_16x16x32_bf16 v[80:83], v[186:189], v[228:231], v[80:83]
	v_mfma_f32_16x16x32_bf16 v[64:67], v[186:189], v[236:239], v[64:67]
	v_mfma_f32_16x16x32_bf16 v[68:71], v[140:143], v[236:239], v[68:71]
	s_setprio 0
	s_barrier
	s_add_i32 s66, s86, s59
	v_lshl_add_u64 v[198:199], v[198:199], 0, s[22:23]
	s_mov_b32 m0, s66
	ds_read_b128 v[190:193], v212 offset:49152
	ds_read_b128 v[194:197], v212 offset:50176
	ds_read_b128 v[214:217], v212 offset:51200
	ds_read_b128 v[218:221], v212 offset:52224
	ds_read_b128 v[224:227], v212 offset:53248
	ds_read_b128 v[228:231], v212 offset:54272
	ds_read_b128 v[232:235], v212 offset:55296
	ds_read_b128 v[236:239], v212 offset:56320
	global_load_lds_dwordx4 v[198:199], off
	s_add_i32 m0, s66, 0x2000
	s_add_u32 s62, s62, 0x40080
	v_lshl_add_u64 v[198:199], v[240:241], 0, s[22:23]
	s_addc_u32 s63, s63, 0
	s_add_i32 s66, s87, s59
	global_load_lds_dwordx4 v[198:199], off
	v_lshl_add_u64 v[198:199], s[62:63], 0, v[152:153]
	s_mov_b32 m0, s66
	s_nop 0
	global_load_lds_dwordx4 v[198:199], off
	v_lshl_add_u64 v[198:199], s[62:63], 0, v[172:173]
	s_add_i32 m0, s66, 0x2000
	s_nop 0
	global_load_lds_dwordx4 v[198:199], off
	v_lshl_add_u64 v[198:199], v[242:243], 0, s[22:23]
	s_mov_b32 m0, s77
	s_nop 0
	global_load_lds_dwordx4 v[198:199], off
	v_lshl_add_u64 v[198:199], v[244:245], 0, s[22:23]
	s_mov_b32 m0, s78
	s_nop 0
	global_load_lds_dwordx4 v[198:199], off
	s_waitcnt vmcnt(8)
	s_waitcnt lgkmcnt(0)
	s_barrier
	s_setprio 1
	s_waitcnt lgkmcnt(0)
	v_mfma_f32_16x16x32_bf16 v[60:63], v[112:115], v[190:193], v[60:63]
	v_mfma_f32_16x16x32_bf16 v[56:59], v[120:123], v[190:193], v[56:59]
	v_mfma_f32_16x16x32_bf16 v[40:43], v[120:123], v[214:217], v[40:43]
	v_mfma_f32_16x16x32_bf16 v[44:47], v[112:115], v[214:217], v[44:47]
	v_mfma_f32_16x16x32_bf16 v[28:31], v[112:115], v[224:227], v[28:31]
	v_mfma_f32_16x16x32_bf16 v[24:27], v[120:123], v[224:227], v[24:27]
	v_mfma_f32_16x16x32_bf16 v[8:11], v[120:123], v[232:235], v[8:11]
	v_mfma_f32_16x16x32_bf16 v[12:15], v[112:115], v[232:235], v[12:15]
	v_mfma_f32_16x16x32_bf16 v[60:63], v[116:119], v[194:197], v[60:63]
	v_mfma_f32_16x16x32_bf16 v[56:59], v[124:127], v[194:197], v[56:59]
	v_mfma_f32_16x16x32_bf16 v[40:43], v[124:127], v[218:221], v[40:43]
	v_mfma_f32_16x16x32_bf16 v[44:47], v[116:119], v[218:221], v[44:47]
	v_mfma_f32_16x16x32_bf16 v[28:31], v[116:119], v[228:231], v[28:31]
	v_mfma_f32_16x16x32_bf16 v[24:27], v[124:127], v[228:231], v[24:27]
	v_mfma_f32_16x16x32_bf16 v[8:11], v[124:127], v[236:239], v[8:11]
	v_mfma_f32_16x16x32_bf16 v[12:15], v[116:119], v[236:239], v[12:15]
	s_setprio 0
	s_setprio 1
	v_mfma_f32_16x16x32_bf16 v[52:55], v[132:135], v[190:193], v[52:55]
	v_mfma_f32_16x16x32_bf16 v[48:51], v[182:185], v[190:193], v[48:51]
	v_mfma_f32_16x16x32_bf16 v[32:35], v[182:185], v[214:217], v[32:35]
	v_mfma_f32_16x16x32_bf16 v[36:39], v[132:135], v[214:217], v[36:39]
	v_mfma_f32_16x16x32_bf16 v[20:23], v[132:135], v[224:227], v[20:23]
	v_mfma_f32_16x16x32_bf16 v[16:19], v[182:185], v[224:227], v[16:19]
	v_mfma_f32_16x16x32_bf16 v[0:3], v[182:185], v[232:235], v[0:3]
	v_mfma_f32_16x16x32_bf16 v[4:7], v[132:135], v[232:235], v[4:7]
	v_mfma_f32_16x16x32_bf16 v[52:55], v[140:143], v[194:197], v[52:55]
	v_mfma_f32_16x16x32_bf16 v[48:51], v[186:189], v[194:197], v[48:51]
	v_mfma_f32_16x16x32_bf16 v[32:35], v[186:189], v[218:221], v[32:35]
	v_mfma_f32_16x16x32_bf16 v[36:39], v[140:143], v[218:221], v[36:39]
	v_mfma_f32_16x16x32_bf16 v[20:23], v[140:143], v[228:231], v[20:23]
	v_mfma_f32_16x16x32_bf16 v[16:19], v[186:189], v[228:231], v[16:19]
	v_mfma_f32_16x16x32_bf16 v[0:3], v[186:189], v[236:239], v[0:3]
	v_mfma_f32_16x16x32_bf16 v[4:7], v[140:143], v[236:239], v[4:7]
	s_setprio 0
	s_barrier
	s_add_i32 s85, s85, 2
	s_add_u32 s83, s83, 0x100
	s_addc_u32 s84, s84, 0
	s_add_u32 s60, s60, 0x100
	s_addc_u32 s61, s61, 0
	s_cmp_gt_u32 s85, 13
	.p2align	6
